# P5: half of each XCD's workgroups run GLA pass 3 before the gathered attention (opposite order), so the latency-bound part overlaps the gather-bound part; plus c3
# baseline (speedup 1.0000x reference)
; __device__ __forceinline__ void attn_phase(const Args& a, unsigned char* lds, int lane, int wave) {
;     bf16_t* P = (bf16_t*)(a.ws + WS_P);
;     const unsigned char* KV8 = a.ws + WS_KV8; const unsigned char* CKV8 = a.ws + WS_CKV8;
;     const unsigned* CAND = (const unsigned*)(a.ws + WS_ACT);
;     unsigned* sel = (unsigned*)(lds + 122880 + wave * 1024);
;     const int gw = blockIdx.x * 8 + wave, NGW = gridDim.x * 8;
;     for (int t = gw; t < TT; t += NGW) {
;         const bool sample = t >= TP; const int bb = sample ? (t - TP) >> 6 : 0;
;         const int c = t >> 6; const int L = sample ? 1088 : 64 * (c + 1);
;         const int nsel = min(256, L);
;         const unsigned* cand = CAND + (size_t)t * 256;
; #pragma unroll
;         for (int j = 0; j < 4; ++j) { const int i = j * 64 + lane; if (i < nsel) sel[i] = cand[i] & 0x3FFFu; }
;         bf16_t* qp = P + (size_t)t * NP + lane * 16;
; __global__ void __launch_bounds__(512, 2) mega_fwd(Args a) {
;     ...
;     if (PHON(5)) {
;         attn_phase(a, lds, lane, wave); __syncthreads(); gla_g3(a, lds, tid, lane, wave);
.LBB0_1859:
	s_cmp_lt_i32 s64, 6
	s_cselect_b64 s[0:1], -1, 0
	s_cmp_gt_i32 s65, 4
	s_cselect_b64 s[2:3], -1, 0
	s_and_b64 s[0:1], s[0:1], s[2:3]
	s_andn2_b64 vcc, exec, s[0:1]
	s_cbranch_vccnz .LBB0_1988
	s_mov_b32 s98, 0
	s_bitcmp1_b32 s74, 3
	s_cbranch_scc0 .Lp5_attn
	s_mov_b32 s98, 1
	s_branch .LBB0_1925
.Lp5_attn:
	s_lshl_b32 s0, s74, 3
	s_add_i32 s2, s96, s0
	s_cmpk_gt_i32 s2, 0x41ff
	s_cbranch_scc1 .LBB0_1925
	s_add_u32 s4, s62, 0x1be00000
	s_addc_u32 s5, s63, 0
	s_add_u32 s6, s62, 0x1df00000
	s_addc_u32 s7, s63, 0
	s_add_u32 s26, s62, 0x6b00000
	v_mov_b32_e32 v57, 0
	s_addc_u32 s27, s63, 0
	s_lshl_b32 s0, s96, 10
	v_lshlrev_b32_e32 v0, 5, v130
	v_mov_b32_e32 v1, v57
	s_add_i32 s29, s0, 0
	v_lshl_add_u64 v[0:1], s[62:63], 0, v[0:1]
	s_mov_b64 s[0:1], 0xad00000
	v_lshl_add_u64 v[58:59], v[0:1], 0, s[0:1]
	v_mbcnt_lo_u32_b32 v0, -1, 0
	s_waitcnt vmcnt(0)
	v_mbcnt_hi_u32_b32 v100, -1, v0
	s_add_i32 s3, s29, 0x1e000
	v_and_b32_e32 v0, 64, v100
	s_lshl_b32 s28, s66, 3
	v_lshlrev_b32_e32 v56, 4, v130
	v_lshl_add_u32 v94, v130, 2, s3
	v_or_b32_e32 v95, 64, v130
	v_or_b32_e32 v96, 0x80, v130
	v_or_b32_e32 v97, 0xc0, v130
	s_add_i32 s29, s29, 0x1e010
	v_mov_b32_e32 v98, 0x3a00
	v_lshlrev_b32_e32 v99, 2, v130
	v_xor_b32_e32 v101, 1, v100
	v_add_u32_e32 v102, 64, v0
	v_xor_b32_e32 v103, 2, v100
	v_xor_b32_e32 v104, 4, v100
	s_branch .Lat_q

; __device__ __forceinline__ void attn_phase(const Args& a, unsigned char* lds, int lane, int wave) {
;     ...
;             for (int i = 0; i < 8; ++i) { float kf[16]; unpack16_fp8(kk[i], kf); float d0 = 0.f, d1 = 0.f;
; #pragma unroll
;                 for (int x = 0; x < 16; x += 2) { d0 += q[x] * kf[x]; d1 += q[x + 1] * kf[x + 1]; }
;                 float d = d0 + d1;
;                 d += __shfl_xor(d, 1); d += __shfl_xor(d, 2); d += __shfl_xor(d, 4); s[i] = d; }
.Lat_blk:
	s_waitcnt vmcnt(30)
	v_cvt_pk_f32_fp8_e32 v[204:205], v132
	v_cvt_pk_f32_fp8_e32 v[206:207], v136
	v_pk_mul_f32 v[220:221], v[204:205], v[78:79]
	v_pk_mul_f32 v[222:223], v[206:207], v[78:79]
	v_cvt_pk_f32_fp8_sdwa v[208:209], v132 src0_sel:WORD_1
	v_cvt_pk_f32_fp8_sdwa v[210:211], v136 src0_sel:WORD_1
	v_pk_fma_f32 v[220:221], v[208:209], v[80:81], v[220:221]
	v_pk_fma_f32 v[222:223], v[210:211], v[80:81], v[222:223]
	v_cvt_pk_f32_fp8_e32 v[212:213], v133
	v_cvt_pk_f32_fp8_e32 v[214:215], v137
	v_pk_fma_f32 v[220:221], v[212:213], v[82:83], v[220:221]
	v_pk_fma_f32 v[222:223], v[214:215], v[82:83], v[222:223]
	v_cvt_pk_f32_fp8_sdwa v[216:217], v133 src0_sel:WORD_1
	v_cvt_pk_f32_fp8_sdwa v[218:219], v137 src0_sel:WORD_1
	v_pk_fma_f32 v[220:221], v[216:217], v[84:85], v[220:221]
	v_pk_fma_f32 v[222:223], v[218:219], v[84:85], v[222:223]
	v_cvt_pk_f32_fp8_e32 v[204:205], v134
	v_cvt_pk_f32_fp8_e32 v[206:207], v138
	v_pk_fma_f32 v[220:221], v[204:205], v[86:87], v[220:221]
	v_pk_fma_f32 v[222:223], v[206:207], v[86:87], v[222:223]
	v_cvt_pk_f32_fp8_sdwa v[208:209], v134 src0_sel:WORD_1
	v_cvt_pk_f32_fp8_sdwa v[210:211], v138 src0_sel:WORD_1
	v_pk_fma_f32 v[220:221], v[208:209], v[88:89], v[220:221]
	v_pk_fma_f32 v[222:223], v[210:211], v[88:89], v[222:223]
	v_cvt_pk_f32_fp8_e32 v[212:213], v135
	v_cvt_pk_f32_fp8_e32 v[214:215], v139
	v_pk_fma_f32 v[220:221], v[212:213], v[90:91], v[220:221]
	v_pk_fma_f32 v[222:223], v[214:215], v[90:91], v[222:223]
	v_cvt_pk_f32_fp8_sdwa v[216:217], v135 src0_sel:WORD_1
	v_cvt_pk_f32_fp8_sdwa v[218:219], v139 src0_sel:WORD_1
	v_pk_fma_f32 v[220:221], v[216:217], v[92:93], v[220:221]
	v_pk_fma_f32 v[222:223], v[218:219], v[92:93], v[222:223]
	s_waitcnt vmcnt(28)
	v_cvt_pk_f32_fp8_e32 v[204:205], v140
	v_cvt_pk_f32_fp8_e32 v[206:207], v144
	v_pk_mul_f32 v[224:225], v[204:205], v[78:79]
	v_pk_mul_f32 v[226:227], v[206:207], v[78:79]
	v_cvt_pk_f32_fp8_sdwa v[208:209], v140 src0_sel:WORD_1
	v_cvt_pk_f32_fp8_sdwa v[210:211], v144 src0_sel:WORD_1
	v_pk_fma_f32 v[224:225], v[208:209], v[80:81], v[224:225]
	v_pk_fma_f32 v[226:227], v[210:211], v[80:81], v[226:227]
	v_cvt_pk_f32_fp8_e32 v[212:213], v141
	v_cvt_pk_f32_fp8_e32 v[214:215], v145
	v_pk_fma_f32 v[224:225], v[212:213], v[82:83], v[224:225]
	v_pk_fma_f32 v[226:227], v[214:215], v[82:83], v[226:227]
	v_cvt_pk_f32_fp8_sdwa v[216:217], v141 src0_sel:WORD_1
	v_cvt_pk_f32_fp8_sdwa v[218:219], v145 src0_sel:WORD_1
	v_pk_fma_f32 v[224:225], v[216:217], v[84:85], v[224:225]
	v_pk_fma_f32 v[226:227], v[218:219], v[84:85], v[226:227]
	v_cvt_pk_f32_fp8_e32 v[204:205], v142
	v_cvt_pk_f32_fp8_e32 v[206:207], v146
	v_pk_fma_f32 v[224:225], v[204:205], v[86:87], v[224:225]
	v_pk_fma_f32 v[226:227], v[206:207], v[86:87], v[226:227]
	v_cvt_pk_f32_fp8_sdwa v[208:209], v142 src0_sel:WORD_1
	v_cvt_pk_f32_fp8_sdwa v[210:211], v146 src0_sel:WORD_1
	v_pk_fma_f32 v[224:225], v[208:209], v[88:89], v[224:225]
	v_pk_fma_f32 v[226:227], v[210:211], v[88:89], v[226:227]
	v_cvt_pk_f32_fp8_e32 v[212:213], v143
	v_cvt_pk_f32_fp8_e32 v[214:215], v147
	v_pk_fma_f32 v[224:225], v[212:213], v[90:91], v[224:225]
	v_pk_fma_f32 v[226:227], v[214:215], v[90:91], v[226:227]
	v_cvt_pk_f32_fp8_sdwa v[216:217], v143 src0_sel:WORD_1
	v_cvt_pk_f32_fp8_sdwa v[218:219], v147 src0_sel:WORD_1
	v_pk_fma_f32 v[224:225], v[216:217], v[92:93], v[224:225]
	v_pk_fma_f32 v[226:227], v[218:219], v[92:93], v[226:227]
	v_add_f32_e32 v110, v220, v221
	v_add_f32_e32 v111, v222, v223
	v_add_f32_e32 v112, v224, v225
	v_add_f32_e32 v113, v226, v227
	v_add_f32_dpp v110, v110, v110 quad_perm:[1,0,3,2] row_mask:0xf bank_mask:0xf
	v_add_f32_dpp v111, v111, v111 quad_perm:[1,0,3,2] row_mask:0xf bank_mask:0xf
	v_add_f32_dpp v112, v112, v112 quad_perm:[1,0,3,2] row_mask:0xf bank_mask:0xf
	v_add_f32_dpp v113, v113, v113 quad_perm:[1,0,3,2] row_mask:0xf bank_mask:0xf
	v_add_f32_dpp v110, v110, v110 quad_perm:[2,3,0,1] row_mask:0xf bank_mask:0xf
	v_add_f32_dpp v111, v111, v111 quad_perm:[2,3,0,1] row_mask:0xf bank_mask:0xf
	v_add_f32_dpp v112, v112, v112 quad_perm:[2,3,0,1] row_mask:0xf bank_mask:0xf
	v_add_f32_dpp v113, v113, v113 quad_perm:[2,3,0,1] row_mask:0xf bank_mask:0xf
	v_add_f32_dpp v110, v110, v110 row_half_mirror row_mask:0xf bank_mask:0xf
	v_add_f32_dpp v111, v111, v111 row_half_mirror row_mask:0xf bank_mask:0xf
	v_add_f32_dpp v112, v112, v112 row_half_mirror row_mask:0xf bank_mask:0xf
	v_add_f32_dpp v113, v113, v113 row_half_mirror row_mask:0xf bank_mask:0xf
	s_waitcnt vmcnt(26)
	v_cvt_pk_f32_fp8_e32 v[204:205], v148
	v_cvt_pk_f32_fp8_e32 v[206:207], v152
	v_pk_mul_f32 v[220:221], v[204:205], v[78:79]
	v_pk_mul_f32 v[222:223], v[206:207], v[78:79]
	v_cvt_pk_f32_fp8_sdwa v[208:209], v148 src0_sel:WORD_1
	v_cvt_pk_f32_fp8_sdwa v[210:211], v152 src0_sel:WORD_1
	v_pk_fma_f32 v[220:221], v[208:209], v[80:81], v[220:221]
	v_pk_fma_f32 v[222:223], v[210:211], v[80:81], v[222:223]
	v_cvt_pk_f32_fp8_e32 v[212:213], v149
	v_cvt_pk_f32_fp8_e32 v[214:215], v153
	v_pk_fma_f32 v[220:221], v[212:213], v[82:83], v[220:221]
	v_pk_fma_f32 v[222:223], v[214:215], v[82:83], v[222:223]
	v_cvt_pk_f32_fp8_sdwa v[216:217], v149 src0_sel:WORD_1
	v_cvt_pk_f32_fp8_sdwa v[218:219], v153 src0_sel:WORD_1
	v_pk_fma_f32 v[220:221], v[216:217], v[84:85], v[220:221]
	v_pk_fma_f32 v[222:223], v[218:219], v[84:85], v[222:223]
	v_cvt_pk_f32_fp8_e32 v[204:205], v150
	v_cvt_pk_f32_fp8_e32 v[206:207], v154
	v_pk_fma_f32 v[220:221], v[204:205], v[86:87], v[220:221]
	v_pk_fma_f32 v[222:223], v[206:207], v[86:87], v[222:223]
	v_cvt_pk_f32_fp8_sdwa v[208:209], v150 src0_sel:WORD_1
	v_cvt_pk_f32_fp8_sdwa v[210:211], v154 src0_sel:WORD_1
	v_pk_fma_f32 v[220:221], v[208:209], v[88:89], v[220:221]
	v_pk_fma_f32 v[222:223], v[210:211], v[88:89], v[222:223]
	v_cvt_pk_f32_fp8_e32 v[212:213], v151
	v_cvt_pk_f32_fp8_e32 v[214:215], v155
	v_pk_fma_f32 v[220:221], v[212:213], v[90:91], v[220:221]
	v_pk_fma_f32 v[222:223], v[214:215], v[90:91], v[222:223]
	v_cvt_pk_f32_fp8_sdwa v[216:217], v151 src0_sel:WORD_1
	v_cvt_pk_f32_fp8_sdwa v[218:219], v155 src0_sel:WORD_1
	v_pk_fma_f32 v[220:221], v[216:217], v[92:93], v[220:221]
	v_pk_fma_f32 v[222:223], v[218:219], v[92:93], v[222:223]
	s_waitcnt vmcnt(24)
; __device__ __forceinline__ void attn_phase(const Args& a, unsigned char* lds, int lane, int wave) {
;     ...
;             for (int i = 0; i < 8; ++i) { float kf[16]; unpack16_fp8(kk[i], kf); float d0 = 0.f, d1 = 0.f;
; #pragma unroll
;                 for (int x = 0; x < 16; x += 2) { d0 += q[x] * kf[x]; d1 += q[x + 1] * kf[x + 1]; }
;                 float d = d0 + d1;
;                 d += __shfl_xor(d, 1); d += __shfl_xor(d, 2); d += __shfl_xor(d, 4); s[i] = d; }
	v_cvt_pk_f32_fp8_e32 v[204:205], v156
	v_cvt_pk_f32_fp8_e32 v[206:207], v160
	v_pk_mul_f32 v[224:225], v[204:205], v[78:79]
	v_pk_mul_f32 v[226:227], v[206:207], v[78:79]
	v_cvt_pk_f32_fp8_sdwa v[208:209], v156 src0_sel:WORD_1
	v_cvt_pk_f32_fp8_sdwa v[210:211], v160 src0_sel:WORD_1
	v_pk_fma_f32 v[224:225], v[208:209], v[80:81], v[224:225]
	v_pk_fma_f32 v[226:227], v[210:211], v[80:81], v[226:227]
	v_cvt_pk_f32_fp8_e32 v[212:213], v157
	v_cvt_pk_f32_fp8_e32 v[214:215], v161
	v_pk_fma_f32 v[224:225], v[212:213], v[82:83], v[224:225]
	v_pk_fma_f32 v[226:227], v[214:215], v[82:83], v[226:227]
	v_cvt_pk_f32_fp8_sdwa v[216:217], v157 src0_sel:WORD_1
	v_cvt_pk_f32_fp8_sdwa v[218:219], v161 src0_sel:WORD_1
	v_pk_fma_f32 v[224:225], v[216:217], v[84:85], v[224:225]
	v_pk_fma_f32 v[226:227], v[218:219], v[84:85], v[226:227]
	v_cvt_pk_f32_fp8_e32 v[204:205], v158
	v_cvt_pk_f32_fp8_e32 v[206:207], v162
	v_pk_fma_f32 v[224:225], v[204:205], v[86:87], v[224:225]
	v_pk_fma_f32 v[226:227], v[206:207], v[86:87], v[226:227]
	v_cvt_pk_f32_fp8_sdwa v[208:209], v158 src0_sel:WORD_1
	v_cvt_pk_f32_fp8_sdwa v[210:211], v162 src0_sel:WORD_1
	v_pk_fma_f32 v[224:225], v[208:209], v[88:89], v[224:225]
	v_pk_fma_f32 v[226:227], v[210:211], v[88:89], v[226:227]
	v_cvt_pk_f32_fp8_e32 v[212:213], v159
	v_cvt_pk_f32_fp8_e32 v[214:215], v163
	v_pk_fma_f32 v[224:225], v[212:213], v[90:91], v[224:225]
	v_pk_fma_f32 v[226:227], v[214:215], v[90:91], v[226:227]
	v_cvt_pk_f32_fp8_sdwa v[216:217], v159 src0_sel:WORD_1
	v_cvt_pk_f32_fp8_sdwa v[218:219], v163 src0_sel:WORD_1
	v_pk_fma_f32 v[224:225], v[216:217], v[92:93], v[224:225]
	v_pk_fma_f32 v[226:227], v[218:219], v[92:93], v[226:227]
	v_add_f32_e32 v114, v220, v221
	v_add_f32_e32 v115, v222, v223
	v_add_f32_e32 v116, v224, v225
	v_add_f32_e32 v117, v226, v227
	v_add_f32_dpp v114, v114, v114 quad_perm:[1,0,3,2] row_mask:0xf bank_mask:0xf
	v_add_f32_dpp v115, v115, v115 quad_perm:[1,0,3,2] row_mask:0xf bank_mask:0xf
	v_add_f32_dpp v116, v116, v116 quad_perm:[1,0,3,2] row_mask:0xf bank_mask:0xf
	v_add_f32_dpp v117, v117, v117 quad_perm:[1,0,3,2] row_mask:0xf bank_mask:0xf
	v_add_f32_dpp v114, v114, v114 quad_perm:[2,3,0,1] row_mask:0xf bank_mask:0xf
	v_add_f32_dpp v115, v115, v115 quad_perm:[2,3,0,1] row_mask:0xf bank_mask:0xf
	v_add_f32_dpp v116, v116, v116 quad_perm:[2,3,0,1] row_mask:0xf bank_mask:0xf
	v_add_f32_dpp v117, v117, v117 quad_perm:[2,3,0,1] row_mask:0xf bank_mask:0xf
	v_add_f32_dpp v114, v114, v114 row_half_mirror row_mask:0xf bank_mask:0xf
	v_add_f32_dpp v115, v115, v115 row_half_mirror row_mask:0xf bank_mask:0xf
	v_add_f32_dpp v116, v116, v116 row_half_mirror row_mask:0xf bank_mask:0xf
	v_add_f32_dpp v117, v117, v117 row_half_mirror row_mask:0xf bank_mask:0xf
	s_waitcnt vmcnt(22)
	v_cvt_pk_f32_fp8_e32 v[204:205], v164
	v_cvt_pk_f32_fp8_e32 v[206:207], v168
	v_pk_mul_f32 v[220:221], v[204:205], v[78:79]
	v_pk_mul_f32 v[222:223], v[206:207], v[78:79]
	v_cvt_pk_f32_fp8_sdwa v[208:209], v164 src0_sel:WORD_1
	v_cvt_pk_f32_fp8_sdwa v[210:211], v168 src0_sel:WORD_1
	v_pk_fma_f32 v[220:221], v[208:209], v[80:81], v[220:221]
	v_pk_fma_f32 v[222:223], v[210:211], v[80:81], v[222:223]
	v_cvt_pk_f32_fp8_e32 v[212:213], v165
	v_cvt_pk_f32_fp8_e32 v[214:215], v169
	v_pk_fma_f32 v[220:221], v[212:213], v[82:83], v[220:221]
	v_pk_fma_f32 v[222:223], v[214:215], v[82:83], v[222:223]
	v_cvt_pk_f32_fp8_sdwa v[216:217], v165 src0_sel:WORD_1
	v_cvt_pk_f32_fp8_sdwa v[218:219], v169 src0_sel:WORD_1
	v_pk_fma_f32 v[220:221], v[216:217], v[84:85], v[220:221]
	v_pk_fma_f32 v[222:223], v[218:219], v[84:85], v[222:223]
	v_cvt_pk_f32_fp8_e32 v[204:205], v166
	v_cvt_pk_f32_fp8_e32 v[206:207], v170
	v_pk_fma_f32 v[220:221], v[204:205], v[86:87], v[220:221]
	v_pk_fma_f32 v[222:223], v[206:207], v[86:87], v[222:223]
	v_cvt_pk_f32_fp8_sdwa v[208:209], v166 src0_sel:WORD_1
	v_cvt_pk_f32_fp8_sdwa v[210:211], v170 src0_sel:WORD_1
	v_pk_fma_f32 v[220:221], v[208:209], v[88:89], v[220:221]
	v_pk_fma_f32 v[222:223], v[210:211], v[88:89], v[222:223]
	v_cvt_pk_f32_fp8_e32 v[212:213], v167
	v_cvt_pk_f32_fp8_e32 v[214:215], v171
	v_pk_fma_f32 v[220:221], v[212:213], v[90:91], v[220:221]
	v_pk_fma_f32 v[222:223], v[214:215], v[90:91], v[222:223]
	v_cvt_pk_f32_fp8_sdwa v[216:217], v167 src0_sel:WORD_1
	v_cvt_pk_f32_fp8_sdwa v[218:219], v171 src0_sel:WORD_1
	v_pk_fma_f32 v[220:221], v[216:217], v[92:93], v[220:221]
	v_pk_fma_f32 v[222:223], v[218:219], v[92:93], v[222:223]
	s_waitcnt vmcnt(20)
; __device__ __forceinline__ void attn_phase(const Args& a, unsigned char* lds, int lane, int wave) {
;     ...
;             for (int i = 0; i < 8; ++i) { float kf[16]; unpack16_fp8(kk[i], kf); float d0 = 0.f, d1 = 0.f;
; #pragma unroll
;                 for (int x = 0; x < 16; x += 2) { d0 += q[x] * kf[x]; d1 += q[x + 1] * kf[x + 1]; }
;                 float d = d0 + d1;
;                 d += __shfl_xor(d, 1); d += __shfl_xor(d, 2); d += __shfl_xor(d, 4); s[i] = d; }
	v_cvt_pk_f32_fp8_e32 v[204:205], v172
	v_cvt_pk_f32_fp8_e32 v[206:207], v176
	v_pk_mul_f32 v[224:225], v[204:205], v[78:79]
	v_pk_mul_f32 v[226:227], v[206:207], v[78:79]
	v_cvt_pk_f32_fp8_sdwa v[208:209], v172 src0_sel:WORD_1
	v_cvt_pk_f32_fp8_sdwa v[210:211], v176 src0_sel:WORD_1
	v_pk_fma_f32 v[224:225], v[208:209], v[80:81], v[224:225]
	v_pk_fma_f32 v[226:227], v[210:211], v[80:81], v[226:227]
	v_cvt_pk_f32_fp8_e32 v[212:213], v173
	v_cvt_pk_f32_fp8_e32 v[214:215], v177
	v_pk_fma_f32 v[224:225], v[212:213], v[82:83], v[224:225]
	v_pk_fma_f32 v[226:227], v[214:215], v[82:83], v[226:227]
	v_cvt_pk_f32_fp8_sdwa v[216:217], v173 src0_sel:WORD_1
	v_cvt_pk_f32_fp8_sdwa v[218:219], v177 src0_sel:WORD_1
	v_pk_fma_f32 v[224:225], v[216:217], v[84:85], v[224:225]
	v_pk_fma_f32 v[226:227], v[218:219], v[84:85], v[226:227]
	v_cvt_pk_f32_fp8_e32 v[204:205], v174
	v_cvt_pk_f32_fp8_e32 v[206:207], v178
	v_pk_fma_f32 v[224:225], v[204:205], v[86:87], v[224:225]
	v_pk_fma_f32 v[226:227], v[206:207], v[86:87], v[226:227]
	v_cvt_pk_f32_fp8_sdwa v[208:209], v174 src0_sel:WORD_1
	v_cvt_pk_f32_fp8_sdwa v[210:211], v178 src0_sel:WORD_1
	v_pk_fma_f32 v[224:225], v[208:209], v[88:89], v[224:225]
	v_pk_fma_f32 v[226:227], v[210:211], v[88:89], v[226:227]
	v_cvt_pk_f32_fp8_e32 v[212:213], v175
	v_cvt_pk_f32_fp8_e32 v[214:215], v179
	v_pk_fma_f32 v[224:225], v[212:213], v[90:91], v[224:225]
	v_pk_fma_f32 v[226:227], v[214:215], v[90:91], v[226:227]
	v_cvt_pk_f32_fp8_sdwa v[216:217], v175 src0_sel:WORD_1
	v_cvt_pk_f32_fp8_sdwa v[218:219], v179 src0_sel:WORD_1
	v_pk_fma_f32 v[224:225], v[216:217], v[92:93], v[224:225]
	v_pk_fma_f32 v[226:227], v[218:219], v[92:93], v[226:227]
	v_add_f32_e32 v118, v220, v221
	v_add_f32_e32 v119, v222, v223
	v_add_f32_e32 v120, v224, v225
	v_add_f32_e32 v121, v226, v227
	v_add_f32_dpp v118, v118, v118 quad_perm:[1,0,3,2] row_mask:0xf bank_mask:0xf
	v_add_f32_dpp v119, v119, v119 quad_perm:[1,0,3,2] row_mask:0xf bank_mask:0xf
	v_add_f32_dpp v120, v120, v120 quad_perm:[1,0,3,2] row_mask:0xf bank_mask:0xf
	v_add_f32_dpp v121, v121, v121 quad_perm:[1,0,3,2] row_mask:0xf bank_mask:0xf
	v_add_f32_dpp v118, v118, v118 quad_perm:[2,3,0,1] row_mask:0xf bank_mask:0xf
	v_add_f32_dpp v119, v119, v119 quad_perm:[2,3,0,1] row_mask:0xf bank_mask:0xf
	v_add_f32_dpp v120, v120, v120 quad_perm:[2,3,0,1] row_mask:0xf bank_mask:0xf
	v_add_f32_dpp v121, v121, v121 quad_perm:[2,3,0,1] row_mask:0xf bank_mask:0xf
	v_add_f32_dpp v118, v118, v118 row_half_mirror row_mask:0xf bank_mask:0xf
	v_add_f32_dpp v119, v119, v119 row_half_mirror row_mask:0xf bank_mask:0xf
	v_add_f32_dpp v120, v120, v120 row_half_mirror row_mask:0xf bank_mask:0xf
	v_add_f32_dpp v121, v121, v121 row_half_mirror row_mask:0xf bank_mask:0xf
	s_waitcnt vmcnt(18)
	v_cvt_pk_f32_fp8_e32 v[204:205], v180
	v_cvt_pk_f32_fp8_e32 v[206:207], v184
	v_pk_mul_f32 v[220:221], v[204:205], v[78:79]
	v_pk_mul_f32 v[222:223], v[206:207], v[78:79]
	v_cvt_pk_f32_fp8_sdwa v[208:209], v180 src0_sel:WORD_1
	v_cvt_pk_f32_fp8_sdwa v[210:211], v184 src0_sel:WORD_1
	v_pk_fma_f32 v[220:221], v[208:209], v[80:81], v[220:221]
	v_pk_fma_f32 v[222:223], v[210:211], v[80:81], v[222:223]
	v_cvt_pk_f32_fp8_e32 v[212:213], v181
	v_cvt_pk_f32_fp8_e32 v[214:215], v185
	v_pk_fma_f32 v[220:221], v[212:213], v[82:83], v[220:221]
	v_pk_fma_f32 v[222:223], v[214:215], v[82:83], v[222:223]
	v_cvt_pk_f32_fp8_sdwa v[216:217], v181 src0_sel:WORD_1
	v_cvt_pk_f32_fp8_sdwa v[218:219], v185 src0_sel:WORD_1
	v_pk_fma_f32 v[220:221], v[216:217], v[84:85], v[220:221]
	v_pk_fma_f32 v[222:223], v[218:219], v[84:85], v[222:223]
	v_cvt_pk_f32_fp8_e32 v[204:205], v182
	v_cvt_pk_f32_fp8_e32 v[206:207], v186
	v_pk_fma_f32 v[220:221], v[204:205], v[86:87], v[220:221]
	v_pk_fma_f32 v[222:223], v[206:207], v[86:87], v[222:223]
	v_cvt_pk_f32_fp8_sdwa v[208:209], v182 src0_sel:WORD_1
	v_cvt_pk_f32_fp8_sdwa v[210:211], v186 src0_sel:WORD_1
	v_pk_fma_f32 v[220:221], v[208:209], v[88:89], v[220:221]
	v_pk_fma_f32 v[222:223], v[210:211], v[88:89], v[222:223]
	v_cvt_pk_f32_fp8_e32 v[212:213], v183
	v_cvt_pk_f32_fp8_e32 v[214:215], v187
	v_pk_fma_f32 v[220:221], v[212:213], v[90:91], v[220:221]
	v_pk_fma_f32 v[222:223], v[214:215], v[90:91], v[222:223]
	v_cvt_pk_f32_fp8_sdwa v[216:217], v183 src0_sel:WORD_1
	v_cvt_pk_f32_fp8_sdwa v[218:219], v187 src0_sel:WORD_1
	v_pk_fma_f32 v[220:221], v[216:217], v[92:93], v[220:221]
	v_pk_fma_f32 v[222:223], v[218:219], v[92:93], v[222:223]
	s_waitcnt vmcnt(16)
; __device__ __forceinline__ void attn_phase(const Args& a, unsigned char* lds, int lane, int wave) {
;     ...
;             const u32x4 ida = *(const u32x4*)(sel + j), idb = *(const u32x4*)(sel + j + 4);
;     ...
;             for (int i = 0; i < 8; ++i) { float kf[16]; unpack16_fp8(kk[i], kf); float d0 = 0.f, d1 = 0.f;
; #pragma unroll
;                 for (int x = 0; x < 16; x += 2) { d0 += q[x] * kf[x]; d1 += q[x + 1] * kf[x + 1]; }
;                 float d = d0 + d1;
;                 d += __shfl_xor(d, 1); d += __shfl_xor(d, 2); d += __shfl_xor(d, 4); s[i] = d; }
;             const float mn = fmaxf(fmaxf(fmaxf(mx, fmaxf(s[0], s[1])), fmaxf(s[2], s[3])), fmaxf(fmaxf(s[4], s[5]), fmaxf(s[6], s[7])));
;             const float al = __builtin_amdgcn_exp2f(mx - mn);
;             float p[8];
; #pragma unroll
;             for (int i = 0; i < 8; ++i) p[i] = __builtin_amdgcn_exp2f(s[i] - mn);
;             l = l * al + ((p[0] + p[1]) + (p[2] + p[3])) + ((p[4] + p[5]) + (p[6] + p[7]));
; #pragma unroll
;             for (int d = 0; d < 16; ++d) o[d] *= al;
	v_cvt_pk_f32_fp8_e32 v[204:205], v188
	v_cvt_pk_f32_fp8_e32 v[206:207], v192
	v_pk_mul_f32 v[224:225], v[204:205], v[78:79]
	v_pk_mul_f32 v[226:227], v[206:207], v[78:79]
	v_cvt_pk_f32_fp8_sdwa v[208:209], v188 src0_sel:WORD_1
	v_cvt_pk_f32_fp8_sdwa v[210:211], v192 src0_sel:WORD_1
	v_pk_fma_f32 v[224:225], v[208:209], v[80:81], v[224:225]
	v_pk_fma_f32 v[226:227], v[210:211], v[80:81], v[226:227]
	v_cvt_pk_f32_fp8_e32 v[212:213], v189
	v_cvt_pk_f32_fp8_e32 v[214:215], v193
	v_pk_fma_f32 v[224:225], v[212:213], v[82:83], v[224:225]
	v_pk_fma_f32 v[226:227], v[214:215], v[82:83], v[226:227]
	v_cvt_pk_f32_fp8_sdwa v[216:217], v189 src0_sel:WORD_1
	v_cvt_pk_f32_fp8_sdwa v[218:219], v193 src0_sel:WORD_1
	v_pk_fma_f32 v[224:225], v[216:217], v[84:85], v[224:225]
	v_pk_fma_f32 v[226:227], v[218:219], v[84:85], v[226:227]
	v_cvt_pk_f32_fp8_e32 v[204:205], v190
	v_cvt_pk_f32_fp8_e32 v[206:207], v194
	v_pk_fma_f32 v[224:225], v[204:205], v[86:87], v[224:225]
	v_pk_fma_f32 v[226:227], v[206:207], v[86:87], v[226:227]
	v_cvt_pk_f32_fp8_sdwa v[208:209], v190 src0_sel:WORD_1
	v_cvt_pk_f32_fp8_sdwa v[210:211], v194 src0_sel:WORD_1
	v_pk_fma_f32 v[224:225], v[208:209], v[88:89], v[224:225]
	v_pk_fma_f32 v[226:227], v[210:211], v[88:89], v[226:227]
	v_cvt_pk_f32_fp8_e32 v[212:213], v191
	v_cvt_pk_f32_fp8_e32 v[214:215], v195
	v_pk_fma_f32 v[224:225], v[212:213], v[90:91], v[224:225]
	v_pk_fma_f32 v[226:227], v[214:215], v[90:91], v[226:227]
	v_cvt_pk_f32_fp8_sdwa v[216:217], v191 src0_sel:WORD_1
	v_cvt_pk_f32_fp8_sdwa v[218:219], v195 src0_sel:WORD_1
	v_pk_fma_f32 v[224:225], v[216:217], v[92:93], v[224:225]
	v_pk_fma_f32 v[226:227], v[218:219], v[92:93], v[226:227]
	v_add_f32_e32 v122, v220, v221
	v_add_f32_e32 v123, v222, v223
	v_add_f32_e32 v124, v224, v225
	v_add_f32_e32 v125, v226, v227
	v_add_f32_dpp v122, v122, v122 quad_perm:[1,0,3,2] row_mask:0xf bank_mask:0xf
	v_add_f32_dpp v123, v123, v123 quad_perm:[1,0,3,2] row_mask:0xf bank_mask:0xf
	v_add_f32_dpp v124, v124, v124 quad_perm:[1,0,3,2] row_mask:0xf bank_mask:0xf
	v_add_f32_dpp v125, v125, v125 quad_perm:[1,0,3,2] row_mask:0xf bank_mask:0xf
	v_add_f32_dpp v122, v122, v122 quad_perm:[2,3,0,1] row_mask:0xf bank_mask:0xf
	v_add_f32_dpp v123, v123, v123 quad_perm:[2,3,0,1] row_mask:0xf bank_mask:0xf
	v_add_f32_dpp v124, v124, v124 quad_perm:[2,3,0,1] row_mask:0xf bank_mask:0xf
	v_add_f32_dpp v125, v125, v125 quad_perm:[2,3,0,1] row_mask:0xf bank_mask:0xf
	v_add_f32_dpp v122, v122, v122 row_half_mirror row_mask:0xf bank_mask:0xf
	v_add_f32_dpp v123, v123, v123 row_half_mirror row_mask:0xf bank_mask:0xf
	v_add_f32_dpp v124, v124, v124 row_half_mirror row_mask:0xf bank_mask:0xf
	v_add_f32_dpp v125, v125, v125 row_half_mirror row_mask:0xf bank_mask:0xf
	v_max3_f32 v228, v110, v111, v112
	v_max3_f32 v229, v113, v114, v115
	v_max3_f32 v230, v116, v117, v118
	v_max3_f32 v231, v119, v120, v121
	v_max3_f32 v232, v122, v123, v124
	v_max3_f32 v233, v125, v109, v228
	v_max3_f32 v234, v229, v230, v231
	v_max3_f32 v235, v232, v233, v234
	v_sub_f32_e32 v236, v109, v235
	v_sub_f32_e32 v110, v110, v235
	v_sub_f32_e32 v111, v111, v235
	v_sub_f32_e32 v112, v112, v235
	v_sub_f32_e32 v113, v113, v235
	v_sub_f32_e32 v114, v114, v235
	v_sub_f32_e32 v115, v115, v235
	v_sub_f32_e32 v116, v116, v235
	v_sub_f32_e32 v117, v117, v235
	v_sub_f32_e32 v118, v118, v235
	v_sub_f32_e32 v119, v119, v235
	v_sub_f32_e32 v120, v120, v235
	v_sub_f32_e32 v121, v121, v235
	v_sub_f32_e32 v122, v122, v235
	v_sub_f32_e32 v123, v123, v235
	v_sub_f32_e32 v124, v124, v235
	v_sub_f32_e32 v125, v125, v235
	v_exp_f32_e32 v244, v236
	v_exp_f32_e32 v110, v110
	v_exp_f32_e32 v111, v111
	v_exp_f32_e32 v112, v112
	v_exp_f32_e32 v113, v113
	v_exp_f32_e32 v114, v114
	v_exp_f32_e32 v115, v115
	v_exp_f32_e32 v116, v116
	v_exp_f32_e32 v117, v117
	v_exp_f32_e32 v118, v118
	v_exp_f32_e32 v119, v119
	v_exp_f32_e32 v120, v120
	v_exp_f32_e32 v121, v121
	v_exp_f32_e32 v122, v122
	v_exp_f32_e32 v123, v123
	v_exp_f32_e32 v124, v124
	v_exp_f32_e32 v125, v125
	v_mov_b32_e32 v109, v235
	v_pk_mul_f32 v[62:63], v[62:63], v[244:245] op_sel_hi:[1,0]
	v_pk_mul_f32 v[64:65], v[64:65], v[244:245] op_sel_hi:[1,0]
	v_pk_mul_f32 v[66:67], v[66:67], v[244:245] op_sel_hi:[1,0]
	v_pk_mul_f32 v[68:69], v[68:69], v[244:245] op_sel_hi:[1,0]
	v_pk_mul_f32 v[70:71], v[70:71], v[244:245] op_sel_hi:[1,0]
	v_pk_mul_f32 v[72:73], v[72:73], v[244:245] op_sel_hi:[1,0]
	v_pk_mul_f32 v[74:75], v[74:75], v[244:245] op_sel_hi:[1,0]
	v_pk_mul_f32 v[76:77], v[76:77], v[244:245] op_sel_hi:[1,0]
	v_add_f32_e32 v228, v110, v111
	v_add_f32_e32 v229, v112, v113
	v_add_f32_e32 v230, v114, v115
	v_add_f32_e32 v231, v116, v117
	v_add_f32_e32 v232, v118, v119
	v_add_f32_e32 v233, v120, v121
	v_add_f32_e32 v234, v122, v123
	v_add_f32_e32 v235, v124, v125
	v_add_f32_e32 v228, v228, v229
	v_add_f32_e32 v230, v230, v231
	v_add_f32_e32 v232, v232, v233
	v_add_f32_e32 v234, v234, v235
	v_add_f32_e32 v228, v228, v230
	v_add_f32_e32 v232, v232, v234
	v_add_f32_e32 v228, v228, v232
	v_fma_f32 v108, v108, v244, v228
	s_add_i32 s31, s31, 64
	v_mov_b32_e32 v246, s31
	ds_read_b128 v[204:207], v246
	ds_read_b128 v[208:211], v246 offset:16
	ds_read_b128 v[212:215], v246 offset:32
	ds_read_b128 v[216:219], v246 offset:48
	s_waitcnt lgkmcnt(0)
; __device__ __forceinline__ void attn_phase(const Args& a, unsigned char* lds, int lane, int wave) {
;     ...
;             const u32x4 ida = *(const u32x4*)(sel + j), idb = *(const u32x4*)(sel + j + 4);
;             u32x4 kk[8], vv[8];
; #pragma unroll
;             for (int i = 0; i < 8; ++i) { const int idx = (int)(i < 4 ? ida[i & 3] : idb[i & 3]); const unsigned char* kp;
;                 if (!sample) kp = KV8 + (size_t)idx * 2048;
;                 else if (idx < 1024) kp = CKV8 + (size_t)(bb * 1024 + idx) * 2048;
;                 else kp = KV8 + (size_t)(TP + bb * 64 + idx - 1024) * 2048;
;                 kk[i] = *(const u32x4*)(kp + lane * 16); vv[i] = *(const u32x4*)(kp + 1024 + lane * 16); }
;     ...
;             for (int i = 0; i < 8; ++i) { float vf[16]; unpack16_fp8(vv[i], vf);
; #pragma unroll
;                 for (int d = 0; d < 16; ++d) o[d] += p[i] * vf[d]; }
	v_readfirstlane_b32 s8, v204
	v_readfirstlane_b32 s9, v205
	v_readfirstlane_b32 s10, v206
	v_readfirstlane_b32 s11, v207
	v_readfirstlane_b32 s12, v208
	v_readfirstlane_b32 s13, v209
	v_readfirstlane_b32 s14, v210
	v_readfirstlane_b32 s15, v211
	v_readfirstlane_b32 s16, v212
	v_readfirstlane_b32 s17, v213
	v_readfirstlane_b32 s18, v214
	v_readfirstlane_b32 s19, v215
	v_readfirstlane_b32 s20, v216
	v_readfirstlane_b32 s21, v217
	v_readfirstlane_b32 s22, v218
	v_readfirstlane_b32 s23, v219
	s_cmp_lt_u32 s8, 0x400
	s_cselect_b32 s24, s6, s4
	s_cselect_b32 s25, s7, s5
	s_lshl_b32 s8, s8, 11
	s_add_u32 s24, s24, s8
	s_addc_u32 s25, s25, 0
	global_load_dwordx4 v[132:135], v56, s[24:25]
	s_cmp_lt_u32 s9, 0x400
	s_cselect_b32 s24, s6, s4
	s_cselect_b32 s25, s7, s5
	s_lshl_b32 s9, s9, 11
	s_add_u32 s24, s24, s9
	s_addc_u32 s25, s25, 0
	global_load_dwordx4 v[136:139], v56, s[24:25]
	s_cmp_lt_u32 s10, 0x400
	s_cselect_b32 s24, s6, s4
	s_cselect_b32 s25, s7, s5
	s_lshl_b32 s10, s10, 11
	s_add_u32 s24, s24, s10
	s_addc_u32 s25, s25, 0
	global_load_dwordx4 v[140:143], v56, s[24:25]
	s_cmp_lt_u32 s11, 0x400
	s_cselect_b32 s24, s6, s4
	s_cselect_b32 s25, s7, s5
	s_lshl_b32 s11, s11, 11
	s_add_u32 s24, s24, s11
	s_addc_u32 s25, s25, 0
	global_load_dwordx4 v[144:147], v56, s[24:25]
	s_cmp_lt_u32 s12, 0x400
	s_cselect_b32 s24, s6, s4
	s_cselect_b32 s25, s7, s5
	s_lshl_b32 s12, s12, 11
	s_add_u32 s24, s24, s12
	s_addc_u32 s25, s25, 0
	global_load_dwordx4 v[148:151], v56, s[24:25]
	s_cmp_lt_u32 s13, 0x400
	s_cselect_b32 s24, s6, s4
	s_cselect_b32 s25, s7, s5
	s_lshl_b32 s13, s13, 11
	s_add_u32 s24, s24, s13
	s_addc_u32 s25, s25, 0
	global_load_dwordx4 v[152:155], v56, s[24:25]
	s_cmp_lt_u32 s14, 0x400
	s_cselect_b32 s24, s6, s4
	s_cselect_b32 s25, s7, s5
	s_lshl_b32 s14, s14, 11
	s_add_u32 s24, s24, s14
	s_addc_u32 s25, s25, 0
	global_load_dwordx4 v[156:159], v56, s[24:25]
	s_cmp_lt_u32 s15, 0x400
	s_cselect_b32 s24, s6, s4
	s_cselect_b32 s25, s7, s5
	s_lshl_b32 s15, s15, 11
	s_add_u32 s24, s24, s15
	s_addc_u32 s25, s25, 0
	global_load_dwordx4 v[160:163], v56, s[24:25]
	s_cmp_lt_u32 s16, 0x400
	s_cselect_b32 s24, s6, s4
	s_cselect_b32 s25, s7, s5
	s_lshl_b32 s16, s16, 11
	s_add_u32 s24, s24, s16
	s_addc_u32 s25, s25, 0
	global_load_dwordx4 v[164:167], v56, s[24:25]
	s_cmp_lt_u32 s17, 0x400
	s_cselect_b32 s24, s6, s4
	s_cselect_b32 s25, s7, s5
	s_lshl_b32 s17, s17, 11
	s_add_u32 s24, s24, s17
	s_addc_u32 s25, s25, 0
	global_load_dwordx4 v[168:171], v56, s[24:25]
	s_cmp_lt_u32 s18, 0x400
	s_cselect_b32 s24, s6, s4
	s_cselect_b32 s25, s7, s5
	s_lshl_b32 s18, s18, 11
	s_add_u32 s24, s24, s18
	s_addc_u32 s25, s25, 0
	global_load_dwordx4 v[172:175], v56, s[24:25]
	s_cmp_lt_u32 s19, 0x400
	s_cselect_b32 s24, s6, s4
	s_cselect_b32 s25, s7, s5
	s_lshl_b32 s19, s19, 11
	s_add_u32 s24, s24, s19
	s_addc_u32 s25, s25, 0
	global_load_dwordx4 v[176:179], v56, s[24:25]
	s_cmp_lt_u32 s20, 0x400
	s_cselect_b32 s24, s6, s4
	s_cselect_b32 s25, s7, s5
	s_lshl_b32 s20, s20, 11
	s_add_u32 s24, s24, s20
	s_addc_u32 s25, s25, 0
	global_load_dwordx4 v[180:183], v56, s[24:25]
	s_cmp_lt_u32 s21, 0x400
	s_cselect_b32 s24, s6, s4
	s_cselect_b32 s25, s7, s5
	s_lshl_b32 s21, s21, 11
	s_add_u32 s24, s24, s21
	s_addc_u32 s25, s25, 0
	global_load_dwordx4 v[184:187], v56, s[24:25]
	s_cmp_lt_u32 s22, 0x400
	s_cselect_b32 s24, s6, s4
	s_cselect_b32 s25, s7, s5
	s_lshl_b32 s22, s22, 11
	s_add_u32 s24, s24, s22
	s_addc_u32 s25, s25, 0
	global_load_dwordx4 v[188:191], v56, s[24:25]
	s_cmp_lt_u32 s23, 0x400
	s_cselect_b32 s24, s6, s4
	s_cselect_b32 s25, s7, s5
	s_lshl_b32 s23, s23, 11
	s_add_u32 s24, s24, s23
	s_addc_u32 s25, s25, 0
	global_load_dwordx4 v[192:195], v56, s[24:25]
	s_waitcnt vmcnt(31)
	v_cvt_pk_f32_fp8_e32 v[204:205], v0
	v_cvt_pk_f32_fp8_sdwa v[206:207], v0 src0_sel:WORD_1
	v_pk_fma_f32 v[62:63], v[204:205], v[110:111], v[62:63] op_sel_hi:[1,0,1]
	v_pk_fma_f32 v[64:65], v[206:207], v[110:111], v[64:65] op_sel_hi:[1,0,1]
	v_cvt_pk_f32_fp8_e32 v[208:209], v1
	v_cvt_pk_f32_fp8_sdwa v[210:211], v1 src0_sel:WORD_1
	v_pk_fma_f32 v[66:67], v[208:209], v[110:111], v[66:67] op_sel_hi:[1,0,1]
	v_pk_fma_f32 v[68:69], v[210:211], v[110:111], v[68:69] op_sel_hi:[1,0,1]
	v_cvt_pk_f32_fp8_e32 v[212:213], v2
	v_cvt_pk_f32_fp8_sdwa v[214:215], v2 src0_sel:WORD_1
	v_pk_fma_f32 v[70:71], v[212:213], v[110:111], v[70:71] op_sel_hi:[1,0,1]
	v_pk_fma_f32 v[72:73], v[214:215], v[110:111], v[72:73] op_sel_hi:[1,0,1]
	v_cvt_pk_f32_fp8_e32 v[216:217], v3
	v_cvt_pk_f32_fp8_sdwa v[218:219], v3 src0_sel:WORD_1
	v_pk_fma_f32 v[74:75], v[216:217], v[110:111], v[74:75] op_sel_hi:[1,0,1]
	v_pk_fma_f32 v[76:77], v[218:219], v[110:111], v[76:77] op_sel_hi:[1,0,1]
	s_waitcnt vmcnt(30)
	v_cvt_pk_f32_fp8_e32 v[204:205], v4
	v_cvt_pk_f32_fp8_sdwa v[206:207], v4 src0_sel:WORD_1
	v_pk_fma_f32 v[62:63], v[204:205], v[110:111], v[62:63] op_sel:[0,1,0] op_sel_hi:[1,1,1]
	v_pk_fma_f32 v[64:65], v[206:207], v[110:111], v[64:65] op_sel:[0,1,0] op_sel_hi:[1,1,1]
	v_cvt_pk_f32_fp8_e32 v[208:209], v5
	v_cvt_pk_f32_fp8_sdwa v[210:211], v5 src0_sel:WORD_1
	v_pk_fma_f32 v[66:67], v[208:209], v[110:111], v[66:67] op_sel:[0,1,0] op_sel_hi:[1,1,1]
	v_pk_fma_f32 v[68:69], v[210:211], v[110:111], v[68:69] op_sel:[0,1,0] op_sel_hi:[1,1,1]
	v_cvt_pk_f32_fp8_e32 v[212:213], v6
	v_cvt_pk_f32_fp8_sdwa v[214:215], v6 src0_sel:WORD_1
	v_pk_fma_f32 v[70:71], v[212:213], v[110:111], v[70:71] op_sel:[0,1,0] op_sel_hi:[1,1,1]
	v_pk_fma_f32 v[72:73], v[214:215], v[110:111], v[72:73] op_sel:[0,1,0] op_sel_hi:[1,1,1]
	v_cvt_pk_f32_fp8_e32 v[216:217], v7
	v_cvt_pk_f32_fp8_sdwa v[218:219], v7 src0_sel:WORD_1
	v_pk_fma_f32 v[74:75], v[216:217], v[110:111], v[74:75] op_sel:[0,1,0] op_sel_hi:[1,1,1]
	v_pk_fma_f32 v[76:77], v[218:219], v[110:111], v[76:77] op_sel:[0,1,0] op_sel_hi:[1,1,1]
	s_waitcnt vmcnt(29)
; __device__ __forceinline__ void attn_phase(const Args& a, unsigned char* lds, int lane, int wave) {
;     ...
;             for (int i = 0; i < 8; ++i) { float vf[16]; unpack16_fp8(vv[i], vf);
; #pragma unroll
;                 for (int d = 0; d < 16; ++d) o[d] += p[i] * vf[d]; }
	v_cvt_pk_f32_fp8_e32 v[204:205], v8
	v_cvt_pk_f32_fp8_sdwa v[206:207], v8 src0_sel:WORD_1
	v_pk_fma_f32 v[62:63], v[204:205], v[112:113], v[62:63] op_sel_hi:[1,0,1]
	v_pk_fma_f32 v[64:65], v[206:207], v[112:113], v[64:65] op_sel_hi:[1,0,1]
	v_cvt_pk_f32_fp8_e32 v[208:209], v9
	v_cvt_pk_f32_fp8_sdwa v[210:211], v9 src0_sel:WORD_1
	v_pk_fma_f32 v[66:67], v[208:209], v[112:113], v[66:67] op_sel_hi:[1,0,1]
	v_pk_fma_f32 v[68:69], v[210:211], v[112:113], v[68:69] op_sel_hi:[1,0,1]
	v_cvt_pk_f32_fp8_e32 v[212:213], v10
	v_cvt_pk_f32_fp8_sdwa v[214:215], v10 src0_sel:WORD_1
	v_pk_fma_f32 v[70:71], v[212:213], v[112:113], v[70:71] op_sel_hi:[1,0,1]
	v_pk_fma_f32 v[72:73], v[214:215], v[112:113], v[72:73] op_sel_hi:[1,0,1]
	v_cvt_pk_f32_fp8_e32 v[216:217], v11
	v_cvt_pk_f32_fp8_sdwa v[218:219], v11 src0_sel:WORD_1
	v_pk_fma_f32 v[74:75], v[216:217], v[112:113], v[74:75] op_sel_hi:[1,0,1]
	v_pk_fma_f32 v[76:77], v[218:219], v[112:113], v[76:77] op_sel_hi:[1,0,1]
	s_waitcnt vmcnt(28)
	v_cvt_pk_f32_fp8_e32 v[204:205], v12
	v_cvt_pk_f32_fp8_sdwa v[206:207], v12 src0_sel:WORD_1
	v_pk_fma_f32 v[62:63], v[204:205], v[112:113], v[62:63] op_sel:[0,1,0] op_sel_hi:[1,1,1]
	v_pk_fma_f32 v[64:65], v[206:207], v[112:113], v[64:65] op_sel:[0,1,0] op_sel_hi:[1,1,1]
	v_cvt_pk_f32_fp8_e32 v[208:209], v13
	v_cvt_pk_f32_fp8_sdwa v[210:211], v13 src0_sel:WORD_1
	v_pk_fma_f32 v[66:67], v[208:209], v[112:113], v[66:67] op_sel:[0,1,0] op_sel_hi:[1,1,1]
	v_pk_fma_f32 v[68:69], v[210:211], v[112:113], v[68:69] op_sel:[0,1,0] op_sel_hi:[1,1,1]
	v_cvt_pk_f32_fp8_e32 v[212:213], v14
	v_cvt_pk_f32_fp8_sdwa v[214:215], v14 src0_sel:WORD_1
	v_pk_fma_f32 v[70:71], v[212:213], v[112:113], v[70:71] op_sel:[0,1,0] op_sel_hi:[1,1,1]
	v_pk_fma_f32 v[72:73], v[214:215], v[112:113], v[72:73] op_sel:[0,1,0] op_sel_hi:[1,1,1]
	v_cvt_pk_f32_fp8_e32 v[216:217], v15
	v_cvt_pk_f32_fp8_sdwa v[218:219], v15 src0_sel:WORD_1
	v_pk_fma_f32 v[74:75], v[216:217], v[112:113], v[74:75] op_sel:[0,1,0] op_sel_hi:[1,1,1]
	v_pk_fma_f32 v[76:77], v[218:219], v[112:113], v[76:77] op_sel:[0,1,0] op_sel_hi:[1,1,1]
	s_waitcnt vmcnt(27)
	v_cvt_pk_f32_fp8_e32 v[204:205], v16
	v_cvt_pk_f32_fp8_sdwa v[206:207], v16 src0_sel:WORD_1
	v_pk_fma_f32 v[62:63], v[204:205], v[114:115], v[62:63] op_sel_hi:[1,0,1]
	v_pk_fma_f32 v[64:65], v[206:207], v[114:115], v[64:65] op_sel_hi:[1,0,1]
	v_cvt_pk_f32_fp8_e32 v[208:209], v17
	v_cvt_pk_f32_fp8_sdwa v[210:211], v17 src0_sel:WORD_1
	v_pk_fma_f32 v[66:67], v[208:209], v[114:115], v[66:67] op_sel_hi:[1,0,1]
	v_pk_fma_f32 v[68:69], v[210:211], v[114:115], v[68:69] op_sel_hi:[1,0,1]
	v_cvt_pk_f32_fp8_e32 v[212:213], v18
	v_cvt_pk_f32_fp8_sdwa v[214:215], v18 src0_sel:WORD_1
	v_pk_fma_f32 v[70:71], v[212:213], v[114:115], v[70:71] op_sel_hi:[1,0,1]
	v_pk_fma_f32 v[72:73], v[214:215], v[114:115], v[72:73] op_sel_hi:[1,0,1]
	v_cvt_pk_f32_fp8_e32 v[216:217], v19
	v_cvt_pk_f32_fp8_sdwa v[218:219], v19 src0_sel:WORD_1
	v_pk_fma_f32 v[74:75], v[216:217], v[114:115], v[74:75] op_sel_hi:[1,0,1]
	v_pk_fma_f32 v[76:77], v[218:219], v[114:115], v[76:77] op_sel_hi:[1,0,1]
	s_waitcnt vmcnt(26)
	v_cvt_pk_f32_fp8_e32 v[204:205], v20
	v_cvt_pk_f32_fp8_sdwa v[206:207], v20 src0_sel:WORD_1
	v_pk_fma_f32 v[62:63], v[204:205], v[114:115], v[62:63] op_sel:[0,1,0] op_sel_hi:[1,1,1]
	v_pk_fma_f32 v[64:65], v[206:207], v[114:115], v[64:65] op_sel:[0,1,0] op_sel_hi:[1,1,1]
	v_cvt_pk_f32_fp8_e32 v[208:209], v21
	v_cvt_pk_f32_fp8_sdwa v[210:211], v21 src0_sel:WORD_1
	v_pk_fma_f32 v[66:67], v[208:209], v[114:115], v[66:67] op_sel:[0,1,0] op_sel_hi:[1,1,1]
	v_pk_fma_f32 v[68:69], v[210:211], v[114:115], v[68:69] op_sel:[0,1,0] op_sel_hi:[1,1,1]
	v_cvt_pk_f32_fp8_e32 v[212:213], v22
	v_cvt_pk_f32_fp8_sdwa v[214:215], v22 src0_sel:WORD_1
	v_pk_fma_f32 v[70:71], v[212:213], v[114:115], v[70:71] op_sel:[0,1,0] op_sel_hi:[1,1,1]
	v_pk_fma_f32 v[72:73], v[214:215], v[114:115], v[72:73] op_sel:[0,1,0] op_sel_hi:[1,1,1]
	v_cvt_pk_f32_fp8_e32 v[216:217], v23
	v_cvt_pk_f32_fp8_sdwa v[218:219], v23 src0_sel:WORD_1
	v_pk_fma_f32 v[74:75], v[216:217], v[114:115], v[74:75] op_sel:[0,1,0] op_sel_hi:[1,1,1]
	v_pk_fma_f32 v[76:77], v[218:219], v[114:115], v[76:77] op_sel:[0,1,0] op_sel_hi:[1,1,1]
	s_waitcnt vmcnt(25)
	v_cvt_pk_f32_fp8_e32 v[204:205], v24
	v_cvt_pk_f32_fp8_sdwa v[206:207], v24 src0_sel:WORD_1
	v_pk_fma_f32 v[62:63], v[204:205], v[116:117], v[62:63] op_sel_hi:[1,0,1]
	v_pk_fma_f32 v[64:65], v[206:207], v[116:117], v[64:65] op_sel_hi:[1,0,1]
	v_cvt_pk_f32_fp8_e32 v[208:209], v25
	v_cvt_pk_f32_fp8_sdwa v[210:211], v25 src0_sel:WORD_1
	v_pk_fma_f32 v[66:67], v[208:209], v[116:117], v[66:67] op_sel_hi:[1,0,1]
	v_pk_fma_f32 v[68:69], v[210:211], v[116:117], v[68:69] op_sel_hi:[1,0,1]
	v_cvt_pk_f32_fp8_e32 v[212:213], v26
	v_cvt_pk_f32_fp8_sdwa v[214:215], v26 src0_sel:WORD_1
	v_pk_fma_f32 v[70:71], v[212:213], v[116:117], v[70:71] op_sel_hi:[1,0,1]
	v_pk_fma_f32 v[72:73], v[214:215], v[116:117], v[72:73] op_sel_hi:[1,0,1]
	v_cvt_pk_f32_fp8_e32 v[216:217], v27
	v_cvt_pk_f32_fp8_sdwa v[218:219], v27 src0_sel:WORD_1
	v_pk_fma_f32 v[74:75], v[216:217], v[116:117], v[74:75] op_sel_hi:[1,0,1]
	v_pk_fma_f32 v[76:77], v[218:219], v[116:117], v[76:77] op_sel_hi:[1,0,1]
	s_waitcnt vmcnt(24)
; __device__ __forceinline__ void attn_phase(const Args& a, unsigned char* lds, int lane, int wave) {
;     ...
;             for (int i = 0; i < 8; ++i) { float vf[16]; unpack16_fp8(vv[i], vf);
; #pragma unroll
;                 for (int d = 0; d < 16; ++d) o[d] += p[i] * vf[d]; }
	v_cvt_pk_f32_fp8_e32 v[204:205], v28
	v_cvt_pk_f32_fp8_sdwa v[206:207], v28 src0_sel:WORD_1
	v_pk_fma_f32 v[62:63], v[204:205], v[116:117], v[62:63] op_sel:[0,1,0] op_sel_hi:[1,1,1]
	v_pk_fma_f32 v[64:65], v[206:207], v[116:117], v[64:65] op_sel:[0,1,0] op_sel_hi:[1,1,1]
	v_cvt_pk_f32_fp8_e32 v[208:209], v29
	v_cvt_pk_f32_fp8_sdwa v[210:211], v29 src0_sel:WORD_1
	v_pk_fma_f32 v[66:67], v[208:209], v[116:117], v[66:67] op_sel:[0,1,0] op_sel_hi:[1,1,1]
	v_pk_fma_f32 v[68:69], v[210:211], v[116:117], v[68:69] op_sel:[0,1,0] op_sel_hi:[1,1,1]
	v_cvt_pk_f32_fp8_e32 v[212:213], v30
	v_cvt_pk_f32_fp8_sdwa v[214:215], v30 src0_sel:WORD_1
	v_pk_fma_f32 v[70:71], v[212:213], v[116:117], v[70:71] op_sel:[0,1,0] op_sel_hi:[1,1,1]
	v_pk_fma_f32 v[72:73], v[214:215], v[116:117], v[72:73] op_sel:[0,1,0] op_sel_hi:[1,1,1]
	v_cvt_pk_f32_fp8_e32 v[216:217], v31
	v_cvt_pk_f32_fp8_sdwa v[218:219], v31 src0_sel:WORD_1
	v_pk_fma_f32 v[74:75], v[216:217], v[116:117], v[74:75] op_sel:[0,1,0] op_sel_hi:[1,1,1]
	v_pk_fma_f32 v[76:77], v[218:219], v[116:117], v[76:77] op_sel:[0,1,0] op_sel_hi:[1,1,1]
	s_waitcnt vmcnt(23)
	v_cvt_pk_f32_fp8_e32 v[204:205], v32
	v_cvt_pk_f32_fp8_sdwa v[206:207], v32 src0_sel:WORD_1
	v_pk_fma_f32 v[62:63], v[204:205], v[118:119], v[62:63] op_sel_hi:[1,0,1]
	v_pk_fma_f32 v[64:65], v[206:207], v[118:119], v[64:65] op_sel_hi:[1,0,1]
	v_cvt_pk_f32_fp8_e32 v[208:209], v33
	v_cvt_pk_f32_fp8_sdwa v[210:211], v33 src0_sel:WORD_1
	v_pk_fma_f32 v[66:67], v[208:209], v[118:119], v[66:67] op_sel_hi:[1,0,1]
	v_pk_fma_f32 v[68:69], v[210:211], v[118:119], v[68:69] op_sel_hi:[1,0,1]
	v_cvt_pk_f32_fp8_e32 v[212:213], v34
	v_cvt_pk_f32_fp8_sdwa v[214:215], v34 src0_sel:WORD_1
	v_pk_fma_f32 v[70:71], v[212:213], v[118:119], v[70:71] op_sel_hi:[1,0,1]
	v_pk_fma_f32 v[72:73], v[214:215], v[118:119], v[72:73] op_sel_hi:[1,0,1]
	v_cvt_pk_f32_fp8_e32 v[216:217], v35
	v_cvt_pk_f32_fp8_sdwa v[218:219], v35 src0_sel:WORD_1
	v_pk_fma_f32 v[74:75], v[216:217], v[118:119], v[74:75] op_sel_hi:[1,0,1]
	v_pk_fma_f32 v[76:77], v[218:219], v[118:119], v[76:77] op_sel_hi:[1,0,1]
	s_waitcnt vmcnt(22)
	v_cvt_pk_f32_fp8_e32 v[204:205], v36
	v_cvt_pk_f32_fp8_sdwa v[206:207], v36 src0_sel:WORD_1
	v_pk_fma_f32 v[62:63], v[204:205], v[118:119], v[62:63] op_sel:[0,1,0] op_sel_hi:[1,1,1]
	v_pk_fma_f32 v[64:65], v[206:207], v[118:119], v[64:65] op_sel:[0,1,0] op_sel_hi:[1,1,1]
	v_cvt_pk_f32_fp8_e32 v[208:209], v37
	v_cvt_pk_f32_fp8_sdwa v[210:211], v37 src0_sel:WORD_1
	v_pk_fma_f32 v[66:67], v[208:209], v[118:119], v[66:67] op_sel:[0,1,0] op_sel_hi:[1,1,1]
	v_pk_fma_f32 v[68:69], v[210:211], v[118:119], v[68:69] op_sel:[0,1,0] op_sel_hi:[1,1,1]
	v_cvt_pk_f32_fp8_e32 v[212:213], v38
	v_cvt_pk_f32_fp8_sdwa v[214:215], v38 src0_sel:WORD_1
	v_pk_fma_f32 v[70:71], v[212:213], v[118:119], v[70:71] op_sel:[0,1,0] op_sel_hi:[1,1,1]
	v_pk_fma_f32 v[72:73], v[214:215], v[118:119], v[72:73] op_sel:[0,1,0] op_sel_hi:[1,1,1]
	v_cvt_pk_f32_fp8_e32 v[216:217], v39
	v_cvt_pk_f32_fp8_sdwa v[218:219], v39 src0_sel:WORD_1
	v_pk_fma_f32 v[74:75], v[216:217], v[118:119], v[74:75] op_sel:[0,1,0] op_sel_hi:[1,1,1]
	v_pk_fma_f32 v[76:77], v[218:219], v[118:119], v[76:77] op_sel:[0,1,0] op_sel_hi:[1,1,1]
	s_waitcnt vmcnt(21)
	v_cvt_pk_f32_fp8_e32 v[204:205], v40
	v_cvt_pk_f32_fp8_sdwa v[206:207], v40 src0_sel:WORD_1
	v_pk_fma_f32 v[62:63], v[204:205], v[120:121], v[62:63] op_sel_hi:[1,0,1]
	v_pk_fma_f32 v[64:65], v[206:207], v[120:121], v[64:65] op_sel_hi:[1,0,1]
	v_cvt_pk_f32_fp8_e32 v[208:209], v41
	v_cvt_pk_f32_fp8_sdwa v[210:211], v41 src0_sel:WORD_1
	v_pk_fma_f32 v[66:67], v[208:209], v[120:121], v[66:67] op_sel_hi:[1,0,1]
	v_pk_fma_f32 v[68:69], v[210:211], v[120:121], v[68:69] op_sel_hi:[1,0,1]
	v_cvt_pk_f32_fp8_e32 v[212:213], v42
	v_cvt_pk_f32_fp8_sdwa v[214:215], v42 src0_sel:WORD_1
	v_pk_fma_f32 v[70:71], v[212:213], v[120:121], v[70:71] op_sel_hi:[1,0,1]
	v_pk_fma_f32 v[72:73], v[214:215], v[120:121], v[72:73] op_sel_hi:[1,0,1]
	v_cvt_pk_f32_fp8_e32 v[216:217], v43
	v_cvt_pk_f32_fp8_sdwa v[218:219], v43 src0_sel:WORD_1
	v_pk_fma_f32 v[74:75], v[216:217], v[120:121], v[74:75] op_sel_hi:[1,0,1]
	v_pk_fma_f32 v[76:77], v[218:219], v[120:121], v[76:77] op_sel_hi:[1,0,1]
	s_waitcnt vmcnt(20)
	v_cvt_pk_f32_fp8_e32 v[204:205], v44
	v_cvt_pk_f32_fp8_sdwa v[206:207], v44 src0_sel:WORD_1
	v_pk_fma_f32 v[62:63], v[204:205], v[120:121], v[62:63] op_sel:[0,1,0] op_sel_hi:[1,1,1]
	v_pk_fma_f32 v[64:65], v[206:207], v[120:121], v[64:65] op_sel:[0,1,0] op_sel_hi:[1,1,1]
	v_cvt_pk_f32_fp8_e32 v[208:209], v45
	v_cvt_pk_f32_fp8_sdwa v[210:211], v45 src0_sel:WORD_1
	v_pk_fma_f32 v[66:67], v[208:209], v[120:121], v[66:67] op_sel:[0,1,0] op_sel_hi:[1,1,1]
	v_pk_fma_f32 v[68:69], v[210:211], v[120:121], v[68:69] op_sel:[0,1,0] op_sel_hi:[1,1,1]
	v_cvt_pk_f32_fp8_e32 v[212:213], v46
	v_cvt_pk_f32_fp8_sdwa v[214:215], v46 src0_sel:WORD_1
	v_pk_fma_f32 v[70:71], v[212:213], v[120:121], v[70:71] op_sel:[0,1,0] op_sel_hi:[1,1,1]
	v_pk_fma_f32 v[72:73], v[214:215], v[120:121], v[72:73] op_sel:[0,1,0] op_sel_hi:[1,1,1]
	v_cvt_pk_f32_fp8_e32 v[216:217], v47
	v_cvt_pk_f32_fp8_sdwa v[218:219], v47 src0_sel:WORD_1
	v_pk_fma_f32 v[74:75], v[216:217], v[120:121], v[74:75] op_sel:[0,1,0] op_sel_hi:[1,1,1]
	v_pk_fma_f32 v[76:77], v[218:219], v[120:121], v[76:77] op_sel:[0,1,0] op_sel_hi:[1,1,1]
	s_waitcnt vmcnt(19)
; __device__ __forceinline__ void attn_phase(const Args& a, unsigned char* lds, int lane, int wave) {
;     ...
;             for (int i = 0; i < 8; ++i) { const int idx = (int)(i < 4 ? ida[i & 3] : idb[i & 3]); const unsigned char* kp;
;                 if (!sample) kp = KV8 + (size_t)idx * 2048;
;                 else if (idx < 1024) kp = CKV8 + (size_t)(bb * 1024 + idx) * 2048;
;                 else kp = KV8 + (size_t)(TP + bb * 64 + idx - 1024) * 2048;
;                 kk[i] = *(const u32x4*)(kp + lane * 16); vv[i] = *(const u32x4*)(kp + 1024 + lane * 16); }
;     ...
;             for (int i = 0; i < 8; ++i) { float vf[16]; unpack16_fp8(vv[i], vf);
; #pragma unroll
;                 for (int d = 0; d < 16; ++d) o[d] += p[i] * vf[d]; }
	v_cvt_pk_f32_fp8_e32 v[204:205], v48
	v_cvt_pk_f32_fp8_sdwa v[206:207], v48 src0_sel:WORD_1
	v_pk_fma_f32 v[62:63], v[204:205], v[122:123], v[62:63] op_sel_hi:[1,0,1]
	v_pk_fma_f32 v[64:65], v[206:207], v[122:123], v[64:65] op_sel_hi:[1,0,1]
	v_cvt_pk_f32_fp8_e32 v[208:209], v49
	v_cvt_pk_f32_fp8_sdwa v[210:211], v49 src0_sel:WORD_1
	v_pk_fma_f32 v[66:67], v[208:209], v[122:123], v[66:67] op_sel_hi:[1,0,1]
	v_pk_fma_f32 v[68:69], v[210:211], v[122:123], v[68:69] op_sel_hi:[1,0,1]
	v_cvt_pk_f32_fp8_e32 v[212:213], v50
	v_cvt_pk_f32_fp8_sdwa v[214:215], v50 src0_sel:WORD_1
	v_pk_fma_f32 v[70:71], v[212:213], v[122:123], v[70:71] op_sel_hi:[1,0,1]
	v_pk_fma_f32 v[72:73], v[214:215], v[122:123], v[72:73] op_sel_hi:[1,0,1]
	v_cvt_pk_f32_fp8_e32 v[216:217], v51
	v_cvt_pk_f32_fp8_sdwa v[218:219], v51 src0_sel:WORD_1
	v_pk_fma_f32 v[74:75], v[216:217], v[122:123], v[74:75] op_sel_hi:[1,0,1]
	v_pk_fma_f32 v[76:77], v[218:219], v[122:123], v[76:77] op_sel_hi:[1,0,1]
	s_waitcnt vmcnt(18)
	v_cvt_pk_f32_fp8_e32 v[204:205], v52
	v_cvt_pk_f32_fp8_sdwa v[206:207], v52 src0_sel:WORD_1
	v_pk_fma_f32 v[62:63], v[204:205], v[122:123], v[62:63] op_sel:[0,1,0] op_sel_hi:[1,1,1]
	v_pk_fma_f32 v[64:65], v[206:207], v[122:123], v[64:65] op_sel:[0,1,0] op_sel_hi:[1,1,1]
	v_cvt_pk_f32_fp8_e32 v[208:209], v53
	v_cvt_pk_f32_fp8_sdwa v[210:211], v53 src0_sel:WORD_1
	v_pk_fma_f32 v[66:67], v[208:209], v[122:123], v[66:67] op_sel:[0,1,0] op_sel_hi:[1,1,1]
	v_pk_fma_f32 v[68:69], v[210:211], v[122:123], v[68:69] op_sel:[0,1,0] op_sel_hi:[1,1,1]
	v_cvt_pk_f32_fp8_e32 v[212:213], v54
	v_cvt_pk_f32_fp8_sdwa v[214:215], v54 src0_sel:WORD_1
	v_pk_fma_f32 v[70:71], v[212:213], v[122:123], v[70:71] op_sel:[0,1,0] op_sel_hi:[1,1,1]
	v_pk_fma_f32 v[72:73], v[214:215], v[122:123], v[72:73] op_sel:[0,1,0] op_sel_hi:[1,1,1]
	v_cvt_pk_f32_fp8_e32 v[216:217], v55
	v_cvt_pk_f32_fp8_sdwa v[218:219], v55 src0_sel:WORD_1
	v_pk_fma_f32 v[74:75], v[216:217], v[122:123], v[74:75] op_sel:[0,1,0] op_sel_hi:[1,1,1]
	v_pk_fma_f32 v[76:77], v[218:219], v[122:123], v[76:77] op_sel:[0,1,0] op_sel_hi:[1,1,1]
	s_waitcnt vmcnt(17)
	v_cvt_pk_f32_fp8_e32 v[204:205], v196
	v_cvt_pk_f32_fp8_sdwa v[206:207], v196 src0_sel:WORD_1
	v_pk_fma_f32 v[62:63], v[204:205], v[124:125], v[62:63] op_sel_hi:[1,0,1]
	v_pk_fma_f32 v[64:65], v[206:207], v[124:125], v[64:65] op_sel_hi:[1,0,1]
	v_cvt_pk_f32_fp8_e32 v[208:209], v197
	v_cvt_pk_f32_fp8_sdwa v[210:211], v197 src0_sel:WORD_1
	v_pk_fma_f32 v[66:67], v[208:209], v[124:125], v[66:67] op_sel_hi:[1,0,1]
	v_pk_fma_f32 v[68:69], v[210:211], v[124:125], v[68:69] op_sel_hi:[1,0,1]
	v_cvt_pk_f32_fp8_e32 v[212:213], v198
	v_cvt_pk_f32_fp8_sdwa v[214:215], v198 src0_sel:WORD_1
	v_pk_fma_f32 v[70:71], v[212:213], v[124:125], v[70:71] op_sel_hi:[1,0,1]
	v_pk_fma_f32 v[72:73], v[214:215], v[124:125], v[72:73] op_sel_hi:[1,0,1]
	v_cvt_pk_f32_fp8_e32 v[216:217], v199
	v_cvt_pk_f32_fp8_sdwa v[218:219], v199 src0_sel:WORD_1
	v_pk_fma_f32 v[74:75], v[216:217], v[124:125], v[74:75] op_sel_hi:[1,0,1]
	v_pk_fma_f32 v[76:77], v[218:219], v[124:125], v[76:77] op_sel_hi:[1,0,1]
	s_waitcnt vmcnt(16)
	v_cvt_pk_f32_fp8_e32 v[204:205], v200
	v_cvt_pk_f32_fp8_sdwa v[206:207], v200 src0_sel:WORD_1
	v_pk_fma_f32 v[62:63], v[204:205], v[124:125], v[62:63] op_sel:[0,1,0] op_sel_hi:[1,1,1]
	v_pk_fma_f32 v[64:65], v[206:207], v[124:125], v[64:65] op_sel:[0,1,0] op_sel_hi:[1,1,1]
	v_cvt_pk_f32_fp8_e32 v[208:209], v201
	v_cvt_pk_f32_fp8_sdwa v[210:211], v201 src0_sel:WORD_1
	v_pk_fma_f32 v[66:67], v[208:209], v[124:125], v[66:67] op_sel:[0,1,0] op_sel_hi:[1,1,1]
	v_pk_fma_f32 v[68:69], v[210:211], v[124:125], v[68:69] op_sel:[0,1,0] op_sel_hi:[1,1,1]
	v_cvt_pk_f32_fp8_e32 v[212:213], v202
	v_cvt_pk_f32_fp8_sdwa v[214:215], v202 src0_sel:WORD_1
	v_pk_fma_f32 v[70:71], v[212:213], v[124:125], v[70:71] op_sel:[0,1,0] op_sel_hi:[1,1,1]
	v_pk_fma_f32 v[72:73], v[214:215], v[124:125], v[72:73] op_sel:[0,1,0] op_sel_hi:[1,1,1]
	v_cvt_pk_f32_fp8_e32 v[216:217], v203
	v_cvt_pk_f32_fp8_sdwa v[218:219], v203 src0_sel:WORD_1
	v_pk_fma_f32 v[74:75], v[216:217], v[124:125], v[74:75] op_sel:[0,1,0] op_sel_hi:[1,1,1]
	v_pk_fma_f32 v[76:77], v[218:219], v[124:125], v[76:77] op_sel:[0,1,0] op_sel_hi:[1,1,1]
	s_cmp_lt_u32 s8, 0x200000
	s_cselect_b32 s24, s6, s4
	s_cselect_b32 s25, s7, s5
	s_add_u32 s24, s24, s8
	s_addc_u32 s25, s25, 0
	global_load_dwordx4 v[0:3], v56, s[24:25] offset:1024
	s_cmp_lt_u32 s9, 0x200000
	s_cselect_b32 s24, s6, s4
	s_cselect_b32 s25, s7, s5
	s_add_u32 s24, s24, s9
	s_addc_u32 s25, s25, 0
	global_load_dwordx4 v[4:7], v56, s[24:25] offset:1024
	s_cmp_lt_u32 s10, 0x200000
	s_cselect_b32 s24, s6, s4
	s_cselect_b32 s25, s7, s5
	s_add_u32 s24, s24, s10
	s_addc_u32 s25, s25, 0
	global_load_dwordx4 v[8:11], v56, s[24:25] offset:1024
	s_cmp_lt_u32 s11, 0x200000
	s_cselect_b32 s24, s6, s4
	s_cselect_b32 s25, s7, s5
	s_add_u32 s24, s24, s11
	s_addc_u32 s25, s25, 0
	global_load_dwordx4 v[12:15], v56, s[24:25] offset:1024
	s_cmp_lt_u32 s12, 0x200000
	s_cselect_b32 s24, s6, s4
	s_cselect_b32 s25, s7, s5
	s_add_u32 s24, s24, s12
	s_addc_u32 s25, s25, 0
	global_load_dwordx4 v[16:19], v56, s[24:25] offset:1024
	s_cmp_lt_u32 s13, 0x200000
	s_cselect_b32 s24, s6, s4
	s_cselect_b32 s25, s7, s5
	s_add_u32 s24, s24, s13
	s_addc_u32 s25, s25, 0
	global_load_dwordx4 v[20:23], v56, s[24:25] offset:1024
	s_cmp_lt_u32 s14, 0x200000
	s_cselect_b32 s24, s6, s4
	s_cselect_b32 s25, s7, s5
	s_add_u32 s24, s24, s14
	s_addc_u32 s25, s25, 0
	global_load_dwordx4 v[24:27], v56, s[24:25] offset:1024
	s_cmp_lt_u32 s15, 0x200000
	s_cselect_b32 s24, s6, s4
	s_cselect_b32 s25, s7, s5
	s_add_u32 s24, s24, s15
	s_addc_u32 s25, s25, 0
; __device__ __forceinline__ void attn_phase(const Args& a, unsigned char* lds, int lane, int wave) {
;     ...
;             for (int i = 0; i < 8; ++i) { const int idx = (int)(i < 4 ? ida[i & 3] : idb[i & 3]); const unsigned char* kp;
;                 if (!sample) kp = KV8 + (size_t)idx * 2048;
;                 else if (idx < 1024) kp = CKV8 + (size_t)(bb * 1024 + idx) * 2048;
;                 else kp = KV8 + (size_t)(TP + bb * 64 + idx - 1024) * 2048;
;                 kk[i] = *(const u32x4*)(kp + lane * 16); vv[i] = *(const u32x4*)(kp + 1024 + lane * 16); }
;     ...
;             for (int i = 0; i < 8; ++i) { float kf[16]; unpack16_fp8(kk[i], kf); float d0 = 0.f, d1 = 0.f;
; #pragma unroll
;                 for (int x = 0; x < 16; x += 2) { d0 += q[x] * kf[x]; d1 += q[x + 1] * kf[x + 1]; }
;                 float d = d0 + d1;
;                 d += __shfl_xor(d, 1); d += __shfl_xor(d, 2); d += __shfl_xor(d, 4); s[i] = d; }
	global_load_dwordx4 v[28:31], v56, s[24:25] offset:1024
	s_cmp_lt_u32 s16, 0x200000
	s_cselect_b32 s24, s6, s4
	s_cselect_b32 s25, s7, s5
	s_add_u32 s24, s24, s16
	s_addc_u32 s25, s25, 0
	global_load_dwordx4 v[32:35], v56, s[24:25] offset:1024
	s_cmp_lt_u32 s17, 0x200000
	s_cselect_b32 s24, s6, s4
	s_cselect_b32 s25, s7, s5
	s_add_u32 s24, s24, s17
	s_addc_u32 s25, s25, 0
	global_load_dwordx4 v[36:39], v56, s[24:25] offset:1024
	s_cmp_lt_u32 s18, 0x200000
	s_cselect_b32 s24, s6, s4
	s_cselect_b32 s25, s7, s5
	s_add_u32 s24, s24, s18
	s_addc_u32 s25, s25, 0
	global_load_dwordx4 v[40:43], v56, s[24:25] offset:1024
	s_cmp_lt_u32 s19, 0x200000
	s_cselect_b32 s24, s6, s4
	s_cselect_b32 s25, s7, s5
	s_add_u32 s24, s24, s19
	s_addc_u32 s25, s25, 0
	global_load_dwordx4 v[44:47], v56, s[24:25] offset:1024
	s_cmp_lt_u32 s20, 0x200000
	s_cselect_b32 s24, s6, s4
	s_cselect_b32 s25, s7, s5
	s_add_u32 s24, s24, s20
	s_addc_u32 s25, s25, 0
	global_load_dwordx4 v[48:51], v56, s[24:25] offset:1024
	s_cmp_lt_u32 s21, 0x200000
	s_cselect_b32 s24, s6, s4
	s_cselect_b32 s25, s7, s5
	s_add_u32 s24, s24, s21
	s_addc_u32 s25, s25, 0
	global_load_dwordx4 v[52:55], v56, s[24:25] offset:1024
	s_cmp_lt_u32 s22, 0x200000
	s_cselect_b32 s24, s6, s4
	s_cselect_b32 s25, s7, s5
	s_add_u32 s24, s24, s22
	s_addc_u32 s25, s25, 0
	global_load_dwordx4 v[196:199], v56, s[24:25] offset:1024
	s_cmp_lt_u32 s23, 0x200000
	s_cselect_b32 s24, s6, s4
	s_cselect_b32 s25, s7, s5
	s_add_u32 s24, s24, s23
	s_addc_u32 s25, s25, 0
	global_load_dwordx4 v[200:203], v56, s[24:25] offset:1024
	s_add_i32 s3, s3, -1
	s_cmp_lg_u32 s3, 0
	s_cbranch_scc1 .Lat_blk
	s_waitcnt vmcnt(30)
	v_cvt_pk_f32_fp8_e32 v[204:205], v132
	v_cvt_pk_f32_fp8_e32 v[206:207], v136
	v_pk_mul_f32 v[220:221], v[204:205], v[78:79]
	v_pk_mul_f32 v[222:223], v[206:207], v[78:79]
	v_cvt_pk_f32_fp8_sdwa v[208:209], v132 src0_sel:WORD_1
	v_cvt_pk_f32_fp8_sdwa v[210:211], v136 src0_sel:WORD_1
	v_pk_fma_f32 v[220:221], v[208:209], v[80:81], v[220:221]
	v_pk_fma_f32 v[222:223], v[210:211], v[80:81], v[222:223]
	v_cvt_pk_f32_fp8_e32 v[212:213], v133
	v_cvt_pk_f32_fp8_e32 v[214:215], v137
	v_pk_fma_f32 v[220:221], v[212:213], v[82:83], v[220:221]
	v_pk_fma_f32 v[222:223], v[214:215], v[82:83], v[222:223]
	v_cvt_pk_f32_fp8_sdwa v[216:217], v133 src0_sel:WORD_1
	v_cvt_pk_f32_fp8_sdwa v[218:219], v137 src0_sel:WORD_1
	v_pk_fma_f32 v[220:221], v[216:217], v[84:85], v[220:221]
	v_pk_fma_f32 v[222:223], v[218:219], v[84:85], v[222:223]
	v_cvt_pk_f32_fp8_e32 v[204:205], v134
	v_cvt_pk_f32_fp8_e32 v[206:207], v138
	v_pk_fma_f32 v[220:221], v[204:205], v[86:87], v[220:221]
	v_pk_fma_f32 v[222:223], v[206:207], v[86:87], v[222:223]
	v_cvt_pk_f32_fp8_sdwa v[208:209], v134 src0_sel:WORD_1
	v_cvt_pk_f32_fp8_sdwa v[210:211], v138 src0_sel:WORD_1
	v_pk_fma_f32 v[220:221], v[208:209], v[88:89], v[220:221]
	v_pk_fma_f32 v[222:223], v[210:211], v[88:89], v[222:223]
	v_cvt_pk_f32_fp8_e32 v[212:213], v135
	v_cvt_pk_f32_fp8_e32 v[214:215], v139
	v_pk_fma_f32 v[220:221], v[212:213], v[90:91], v[220:221]
	v_pk_fma_f32 v[222:223], v[214:215], v[90:91], v[222:223]
	v_cvt_pk_f32_fp8_sdwa v[216:217], v135 src0_sel:WORD_1
	v_cvt_pk_f32_fp8_sdwa v[218:219], v139 src0_sel:WORD_1
	v_pk_fma_f32 v[220:221], v[216:217], v[92:93], v[220:221]
	v_pk_fma_f32 v[222:223], v[218:219], v[92:93], v[222:223]
	s_waitcnt vmcnt(28)
	v_cvt_pk_f32_fp8_e32 v[204:205], v140
	v_cvt_pk_f32_fp8_e32 v[206:207], v144
	v_pk_mul_f32 v[224:225], v[204:205], v[78:79]
	v_pk_mul_f32 v[226:227], v[206:207], v[78:79]
	v_cvt_pk_f32_fp8_sdwa v[208:209], v140 src0_sel:WORD_1
	v_cvt_pk_f32_fp8_sdwa v[210:211], v144 src0_sel:WORD_1
	v_pk_fma_f32 v[224:225], v[208:209], v[80:81], v[224:225]
	v_pk_fma_f32 v[226:227], v[210:211], v[80:81], v[226:227]
	v_cvt_pk_f32_fp8_e32 v[212:213], v141
	v_cvt_pk_f32_fp8_e32 v[214:215], v145
	v_pk_fma_f32 v[224:225], v[212:213], v[82:83], v[224:225]
	v_pk_fma_f32 v[226:227], v[214:215], v[82:83], v[226:227]
	v_cvt_pk_f32_fp8_sdwa v[216:217], v141 src0_sel:WORD_1
	v_cvt_pk_f32_fp8_sdwa v[218:219], v145 src0_sel:WORD_1
	v_pk_fma_f32 v[224:225], v[216:217], v[84:85], v[224:225]
	v_pk_fma_f32 v[226:227], v[218:219], v[84:85], v[226:227]
	v_cvt_pk_f32_fp8_e32 v[204:205], v142
	v_cvt_pk_f32_fp8_e32 v[206:207], v146
	v_pk_fma_f32 v[224:225], v[204:205], v[86:87], v[224:225]
	v_pk_fma_f32 v[226:227], v[206:207], v[86:87], v[226:227]
	v_cvt_pk_f32_fp8_sdwa v[208:209], v142 src0_sel:WORD_1
	v_cvt_pk_f32_fp8_sdwa v[210:211], v146 src0_sel:WORD_1
	v_pk_fma_f32 v[224:225], v[208:209], v[88:89], v[224:225]
	v_pk_fma_f32 v[226:227], v[210:211], v[88:89], v[226:227]
	v_cvt_pk_f32_fp8_e32 v[212:213], v143
	v_cvt_pk_f32_fp8_e32 v[214:215], v147
	v_pk_fma_f32 v[224:225], v[212:213], v[90:91], v[224:225]
	v_pk_fma_f32 v[226:227], v[214:215], v[90:91], v[226:227]
	v_cvt_pk_f32_fp8_sdwa v[216:217], v143 src0_sel:WORD_1
	v_cvt_pk_f32_fp8_sdwa v[218:219], v147 src0_sel:WORD_1
	v_pk_fma_f32 v[224:225], v[216:217], v[92:93], v[224:225]
	v_pk_fma_f32 v[226:227], v[218:219], v[92:93], v[226:227]
	v_add_f32_e32 v110, v220, v221
	v_add_f32_e32 v111, v222, v223
	v_add_f32_e32 v112, v224, v225
	v_add_f32_e32 v113, v226, v227
	v_add_f32_dpp v110, v110, v110 quad_perm:[1,0,3,2] row_mask:0xf bank_mask:0xf
	v_add_f32_dpp v111, v111, v111 quad_perm:[1,0,3,2] row_mask:0xf bank_mask:0xf
	v_add_f32_dpp v112, v112, v112 quad_perm:[1,0,3,2] row_mask:0xf bank_mask:0xf
	v_add_f32_dpp v113, v113, v113 quad_perm:[1,0,3,2] row_mask:0xf bank_mask:0xf
	v_add_f32_dpp v110, v110, v110 quad_perm:[2,3,0,1] row_mask:0xf bank_mask:0xf
	v_add_f32_dpp v111, v111, v111 quad_perm:[2,3,0,1] row_mask:0xf bank_mask:0xf
	v_add_f32_dpp v112, v112, v112 quad_perm:[2,3,0,1] row_mask:0xf bank_mask:0xf
	v_add_f32_dpp v113, v113, v113 quad_perm:[2,3,0,1] row_mask:0xf bank_mask:0xf
	v_add_f32_dpp v110, v110, v110 row_half_mirror row_mask:0xf bank_mask:0xf
	v_add_f32_dpp v111, v111, v111 row_half_mirror row_mask:0xf bank_mask:0xf
	v_add_f32_dpp v112, v112, v112 row_half_mirror row_mask:0xf bank_mask:0xf
	v_add_f32_dpp v113, v113, v113 row_half_mirror row_mask:0xf bank_mask:0xf
	s_waitcnt vmcnt(26)
; __device__ __forceinline__ void attn_phase(const Args& a, unsigned char* lds, int lane, int wave) {
;     ...
;             float s[8];
; #pragma unroll
;             for (int i = 0; i < 8; ++i) { float kf[16]; unpack16_fp8(kk[i], kf); float d0 = 0.f, d1 = 0.f;
; #pragma unroll
;                 for (int x = 0; x < 16; x += 2) { d0 += q[x] * kf[x]; d1 += q[x + 1] * kf[x + 1]; }
;                 float d = d0 + d1;
;                 d += __shfl_xor(d, 1); d += __shfl_xor(d, 2); d += __shfl_xor(d, 4); s[i] = d; }
	v_cvt_pk_f32_fp8_e32 v[204:205], v148
	v_cvt_pk_f32_fp8_e32 v[206:207], v152
	v_pk_mul_f32 v[220:221], v[204:205], v[78:79]
	v_pk_mul_f32 v[222:223], v[206:207], v[78:79]
	v_cvt_pk_f32_fp8_sdwa v[208:209], v148 src0_sel:WORD_1
	v_cvt_pk_f32_fp8_sdwa v[210:211], v152 src0_sel:WORD_1
	v_pk_fma_f32 v[220:221], v[208:209], v[80:81], v[220:221]
	v_pk_fma_f32 v[222:223], v[210:211], v[80:81], v[222:223]
	v_cvt_pk_f32_fp8_e32 v[212:213], v149
	v_cvt_pk_f32_fp8_e32 v[214:215], v153
	v_pk_fma_f32 v[220:221], v[212:213], v[82:83], v[220:221]
	v_pk_fma_f32 v[222:223], v[214:215], v[82:83], v[222:223]
	v_cvt_pk_f32_fp8_sdwa v[216:217], v149 src0_sel:WORD_1
	v_cvt_pk_f32_fp8_sdwa v[218:219], v153 src0_sel:WORD_1
	v_pk_fma_f32 v[220:221], v[216:217], v[84:85], v[220:221]
	v_pk_fma_f32 v[222:223], v[218:219], v[84:85], v[222:223]
	v_cvt_pk_f32_fp8_e32 v[204:205], v150
	v_cvt_pk_f32_fp8_e32 v[206:207], v154
	v_pk_fma_f32 v[220:221], v[204:205], v[86:87], v[220:221]
	v_pk_fma_f32 v[222:223], v[206:207], v[86:87], v[222:223]
	v_cvt_pk_f32_fp8_sdwa v[208:209], v150 src0_sel:WORD_1
	v_cvt_pk_f32_fp8_sdwa v[210:211], v154 src0_sel:WORD_1
	v_pk_fma_f32 v[220:221], v[208:209], v[88:89], v[220:221]
	v_pk_fma_f32 v[222:223], v[210:211], v[88:89], v[222:223]
	v_cvt_pk_f32_fp8_e32 v[212:213], v151
	v_cvt_pk_f32_fp8_e32 v[214:215], v155
	v_pk_fma_f32 v[220:221], v[212:213], v[90:91], v[220:221]
	v_pk_fma_f32 v[222:223], v[214:215], v[90:91], v[222:223]
	v_cvt_pk_f32_fp8_sdwa v[216:217], v151 src0_sel:WORD_1
	v_cvt_pk_f32_fp8_sdwa v[218:219], v155 src0_sel:WORD_1
	v_pk_fma_f32 v[220:221], v[216:217], v[92:93], v[220:221]
	v_pk_fma_f32 v[222:223], v[218:219], v[92:93], v[222:223]
	s_waitcnt vmcnt(24)
	v_cvt_pk_f32_fp8_e32 v[204:205], v156
	v_cvt_pk_f32_fp8_e32 v[206:207], v160
	v_pk_mul_f32 v[224:225], v[204:205], v[78:79]
	v_pk_mul_f32 v[226:227], v[206:207], v[78:79]
	v_cvt_pk_f32_fp8_sdwa v[208:209], v156 src0_sel:WORD_1
	v_cvt_pk_f32_fp8_sdwa v[210:211], v160 src0_sel:WORD_1
	v_pk_fma_f32 v[224:225], v[208:209], v[80:81], v[224:225]
	v_pk_fma_f32 v[226:227], v[210:211], v[80:81], v[226:227]
	v_cvt_pk_f32_fp8_e32 v[212:213], v157
	v_cvt_pk_f32_fp8_e32 v[214:215], v161
	v_pk_fma_f32 v[224:225], v[212:213], v[82:83], v[224:225]
	v_pk_fma_f32 v[226:227], v[214:215], v[82:83], v[226:227]
	v_cvt_pk_f32_fp8_sdwa v[216:217], v157 src0_sel:WORD_1
	v_cvt_pk_f32_fp8_sdwa v[218:219], v161 src0_sel:WORD_1
	v_pk_fma_f32 v[224:225], v[216:217], v[84:85], v[224:225]
	v_pk_fma_f32 v[226:227], v[218:219], v[84:85], v[226:227]
	v_cvt_pk_f32_fp8_e32 v[204:205], v158
	v_cvt_pk_f32_fp8_e32 v[206:207], v162
	v_pk_fma_f32 v[224:225], v[204:205], v[86:87], v[224:225]
	v_pk_fma_f32 v[226:227], v[206:207], v[86:87], v[226:227]
	v_cvt_pk_f32_fp8_sdwa v[208:209], v158 src0_sel:WORD_1
	v_cvt_pk_f32_fp8_sdwa v[210:211], v162 src0_sel:WORD_1
	v_pk_fma_f32 v[224:225], v[208:209], v[88:89], v[224:225]
	v_pk_fma_f32 v[226:227], v[210:211], v[88:89], v[226:227]
	v_cvt_pk_f32_fp8_e32 v[212:213], v159
	v_cvt_pk_f32_fp8_e32 v[214:215], v163
	v_pk_fma_f32 v[224:225], v[212:213], v[90:91], v[224:225]
	v_pk_fma_f32 v[226:227], v[214:215], v[90:91], v[226:227]
	v_cvt_pk_f32_fp8_sdwa v[216:217], v159 src0_sel:WORD_1
	v_cvt_pk_f32_fp8_sdwa v[218:219], v163 src0_sel:WORD_1
	v_pk_fma_f32 v[224:225], v[216:217], v[92:93], v[224:225]
	v_pk_fma_f32 v[226:227], v[218:219], v[92:93], v[226:227]
	v_add_f32_e32 v114, v220, v221
	v_add_f32_e32 v115, v222, v223
	v_add_f32_e32 v116, v224, v225
	v_add_f32_e32 v117, v226, v227
	v_add_f32_dpp v114, v114, v114 quad_perm:[1,0,3,2] row_mask:0xf bank_mask:0xf
	v_add_f32_dpp v115, v115, v115 quad_perm:[1,0,3,2] row_mask:0xf bank_mask:0xf
	v_add_f32_dpp v116, v116, v116 quad_perm:[1,0,3,2] row_mask:0xf bank_mask:0xf
	v_add_f32_dpp v117, v117, v117 quad_perm:[1,0,3,2] row_mask:0xf bank_mask:0xf
	v_add_f32_dpp v114, v114, v114 quad_perm:[2,3,0,1] row_mask:0xf bank_mask:0xf
	v_add_f32_dpp v115, v115, v115 quad_perm:[2,3,0,1] row_mask:0xf bank_mask:0xf
	v_add_f32_dpp v116, v116, v116 quad_perm:[2,3,0,1] row_mask:0xf bank_mask:0xf
	v_add_f32_dpp v117, v117, v117 quad_perm:[2,3,0,1] row_mask:0xf bank_mask:0xf
	v_add_f32_dpp v114, v114, v114 row_half_mirror row_mask:0xf bank_mask:0xf
	v_add_f32_dpp v115, v115, v115 row_half_mirror row_mask:0xf bank_mask:0xf
	v_add_f32_dpp v116, v116, v116 row_half_mirror row_mask:0xf bank_mask:0xf
	v_add_f32_dpp v117, v117, v117 row_half_mirror row_mask:0xf bank_mask:0xf
	s_waitcnt vmcnt(22)
	v_cvt_pk_f32_fp8_e32 v[204:205], v164
	v_cvt_pk_f32_fp8_e32 v[206:207], v168
	v_pk_mul_f32 v[220:221], v[204:205], v[78:79]
	v_pk_mul_f32 v[222:223], v[206:207], v[78:79]
	v_cvt_pk_f32_fp8_sdwa v[208:209], v164 src0_sel:WORD_1
	v_cvt_pk_f32_fp8_sdwa v[210:211], v168 src0_sel:WORD_1
	v_pk_fma_f32 v[220:221], v[208:209], v[80:81], v[220:221]
	v_pk_fma_f32 v[222:223], v[210:211], v[80:81], v[222:223]
	v_cvt_pk_f32_fp8_e32 v[212:213], v165
	v_cvt_pk_f32_fp8_e32 v[214:215], v169
	v_pk_fma_f32 v[220:221], v[212:213], v[82:83], v[220:221]
	v_pk_fma_f32 v[222:223], v[214:215], v[82:83], v[222:223]
	v_cvt_pk_f32_fp8_sdwa v[216:217], v165 src0_sel:WORD_1
	v_cvt_pk_f32_fp8_sdwa v[218:219], v169 src0_sel:WORD_1
	v_pk_fma_f32 v[220:221], v[216:217], v[84:85], v[220:221]
	v_pk_fma_f32 v[222:223], v[218:219], v[84:85], v[222:223]
	v_cvt_pk_f32_fp8_e32 v[204:205], v166
	v_cvt_pk_f32_fp8_e32 v[206:207], v170
	v_pk_fma_f32 v[220:221], v[204:205], v[86:87], v[220:221]
	v_pk_fma_f32 v[222:223], v[206:207], v[86:87], v[222:223]
	v_cvt_pk_f32_fp8_sdwa v[208:209], v166 src0_sel:WORD_1
	v_cvt_pk_f32_fp8_sdwa v[210:211], v170 src0_sel:WORD_1
	v_pk_fma_f32 v[220:221], v[208:209], v[88:89], v[220:221]
	v_pk_fma_f32 v[222:223], v[210:211], v[88:89], v[222:223]
	v_cvt_pk_f32_fp8_e32 v[212:213], v167
	v_cvt_pk_f32_fp8_e32 v[214:215], v171
	v_pk_fma_f32 v[220:221], v[212:213], v[90:91], v[220:221]
	v_pk_fma_f32 v[222:223], v[214:215], v[90:91], v[222:223]
	v_cvt_pk_f32_fp8_sdwa v[216:217], v167 src0_sel:WORD_1
	v_cvt_pk_f32_fp8_sdwa v[218:219], v171 src0_sel:WORD_1
	v_pk_fma_f32 v[220:221], v[216:217], v[92:93], v[220:221]
	v_pk_fma_f32 v[222:223], v[218:219], v[92:93], v[222:223]
	s_waitcnt vmcnt(20)
; __device__ __forceinline__ void attn_phase(const Args& a, unsigned char* lds, int lane, int wave) {
;     ...
;             float s[8];
; #pragma unroll
;             for (int i = 0; i < 8; ++i) { float kf[16]; unpack16_fp8(kk[i], kf); float d0 = 0.f, d1 = 0.f;
; #pragma unroll
;                 for (int x = 0; x < 16; x += 2) { d0 += q[x] * kf[x]; d1 += q[x + 1] * kf[x + 1]; }
;                 float d = d0 + d1;
;                 d += __shfl_xor(d, 1); d += __shfl_xor(d, 2); d += __shfl_xor(d, 4); s[i] = d; }
	v_cvt_pk_f32_fp8_e32 v[204:205], v172
	v_cvt_pk_f32_fp8_e32 v[206:207], v176
	v_pk_mul_f32 v[224:225], v[204:205], v[78:79]
	v_pk_mul_f32 v[226:227], v[206:207], v[78:79]
	v_cvt_pk_f32_fp8_sdwa v[208:209], v172 src0_sel:WORD_1
	v_cvt_pk_f32_fp8_sdwa v[210:211], v176 src0_sel:WORD_1
	v_pk_fma_f32 v[224:225], v[208:209], v[80:81], v[224:225]
	v_pk_fma_f32 v[226:227], v[210:211], v[80:81], v[226:227]
	v_cvt_pk_f32_fp8_e32 v[212:213], v173
	v_cvt_pk_f32_fp8_e32 v[214:215], v177
	v_pk_fma_f32 v[224:225], v[212:213], v[82:83], v[224:225]
	v_pk_fma_f32 v[226:227], v[214:215], v[82:83], v[226:227]
	v_cvt_pk_f32_fp8_sdwa v[216:217], v173 src0_sel:WORD_1
	v_cvt_pk_f32_fp8_sdwa v[218:219], v177 src0_sel:WORD_1
	v_pk_fma_f32 v[224:225], v[216:217], v[84:85], v[224:225]
	v_pk_fma_f32 v[226:227], v[218:219], v[84:85], v[226:227]
	v_cvt_pk_f32_fp8_e32 v[204:205], v174
	v_cvt_pk_f32_fp8_e32 v[206:207], v178
	v_pk_fma_f32 v[224:225], v[204:205], v[86:87], v[224:225]
	v_pk_fma_f32 v[226:227], v[206:207], v[86:87], v[226:227]
	v_cvt_pk_f32_fp8_sdwa v[208:209], v174 src0_sel:WORD_1
	v_cvt_pk_f32_fp8_sdwa v[210:211], v178 src0_sel:WORD_1
	v_pk_fma_f32 v[224:225], v[208:209], v[88:89], v[224:225]
	v_pk_fma_f32 v[226:227], v[210:211], v[88:89], v[226:227]
	v_cvt_pk_f32_fp8_e32 v[212:213], v175
	v_cvt_pk_f32_fp8_e32 v[214:215], v179
	v_pk_fma_f32 v[224:225], v[212:213], v[90:91], v[224:225]
	v_pk_fma_f32 v[226:227], v[214:215], v[90:91], v[226:227]
	v_cvt_pk_f32_fp8_sdwa v[216:217], v175 src0_sel:WORD_1
	v_cvt_pk_f32_fp8_sdwa v[218:219], v179 src0_sel:WORD_1
	v_pk_fma_f32 v[224:225], v[216:217], v[92:93], v[224:225]
	v_pk_fma_f32 v[226:227], v[218:219], v[92:93], v[226:227]
	v_add_f32_e32 v118, v220, v221
	v_add_f32_e32 v119, v222, v223
	v_add_f32_e32 v120, v224, v225
	v_add_f32_e32 v121, v226, v227
	v_add_f32_dpp v118, v118, v118 quad_perm:[1,0,3,2] row_mask:0xf bank_mask:0xf
	v_add_f32_dpp v119, v119, v119 quad_perm:[1,0,3,2] row_mask:0xf bank_mask:0xf
	v_add_f32_dpp v120, v120, v120 quad_perm:[1,0,3,2] row_mask:0xf bank_mask:0xf
	v_add_f32_dpp v121, v121, v121 quad_perm:[1,0,3,2] row_mask:0xf bank_mask:0xf
	v_add_f32_dpp v118, v118, v118 quad_perm:[2,3,0,1] row_mask:0xf bank_mask:0xf
	v_add_f32_dpp v119, v119, v119 quad_perm:[2,3,0,1] row_mask:0xf bank_mask:0xf
	v_add_f32_dpp v120, v120, v120 quad_perm:[2,3,0,1] row_mask:0xf bank_mask:0xf
	v_add_f32_dpp v121, v121, v121 quad_perm:[2,3,0,1] row_mask:0xf bank_mask:0xf
	v_add_f32_dpp v118, v118, v118 row_half_mirror row_mask:0xf bank_mask:0xf
	v_add_f32_dpp v119, v119, v119 row_half_mirror row_mask:0xf bank_mask:0xf
	v_add_f32_dpp v120, v120, v120 row_half_mirror row_mask:0xf bank_mask:0xf
	v_add_f32_dpp v121, v121, v121 row_half_mirror row_mask:0xf bank_mask:0xf
	s_waitcnt vmcnt(18)
	v_cvt_pk_f32_fp8_e32 v[204:205], v180
	v_cvt_pk_f32_fp8_e32 v[206:207], v184
	v_pk_mul_f32 v[220:221], v[204:205], v[78:79]
	v_pk_mul_f32 v[222:223], v[206:207], v[78:79]
	v_cvt_pk_f32_fp8_sdwa v[208:209], v180 src0_sel:WORD_1
	v_cvt_pk_f32_fp8_sdwa v[210:211], v184 src0_sel:WORD_1
	v_pk_fma_f32 v[220:221], v[208:209], v[80:81], v[220:221]
	v_pk_fma_f32 v[222:223], v[210:211], v[80:81], v[222:223]
	v_cvt_pk_f32_fp8_e32 v[212:213], v181
	v_cvt_pk_f32_fp8_e32 v[214:215], v185
	v_pk_fma_f32 v[220:221], v[212:213], v[82:83], v[220:221]
	v_pk_fma_f32 v[222:223], v[214:215], v[82:83], v[222:223]
	v_cvt_pk_f32_fp8_sdwa v[216:217], v181 src0_sel:WORD_1
	v_cvt_pk_f32_fp8_sdwa v[218:219], v185 src0_sel:WORD_1
	v_pk_fma_f32 v[220:221], v[216:217], v[84:85], v[220:221]
	v_pk_fma_f32 v[222:223], v[218:219], v[84:85], v[222:223]
	v_cvt_pk_f32_fp8_e32 v[204:205], v182
	v_cvt_pk_f32_fp8_e32 v[206:207], v186
	v_pk_fma_f32 v[220:221], v[204:205], v[86:87], v[220:221]
	v_pk_fma_f32 v[222:223], v[206:207], v[86:87], v[222:223]
	v_cvt_pk_f32_fp8_sdwa v[208:209], v182 src0_sel:WORD_1
	v_cvt_pk_f32_fp8_sdwa v[210:211], v186 src0_sel:WORD_1
	v_pk_fma_f32 v[220:221], v[208:209], v[88:89], v[220:221]
	v_pk_fma_f32 v[222:223], v[210:211], v[88:89], v[222:223]
	v_cvt_pk_f32_fp8_e32 v[212:213], v183
	v_cvt_pk_f32_fp8_e32 v[214:215], v187
	v_pk_fma_f32 v[220:221], v[212:213], v[90:91], v[220:221]
	v_pk_fma_f32 v[222:223], v[214:215], v[90:91], v[222:223]
	v_cvt_pk_f32_fp8_sdwa v[216:217], v183 src0_sel:WORD_1
	v_cvt_pk_f32_fp8_sdwa v[218:219], v187 src0_sel:WORD_1
	v_pk_fma_f32 v[220:221], v[216:217], v[92:93], v[220:221]
	v_pk_fma_f32 v[222:223], v[218:219], v[92:93], v[222:223]
	s_waitcnt vmcnt(16)
; __device__ __forceinline__ void attn_phase(const Args& a, unsigned char* lds, int lane, int wave) {
;     ...
;             float s[8];
; #pragma unroll
;             for (int i = 0; i < 8; ++i) { float kf[16]; unpack16_fp8(kk[i], kf); float d0 = 0.f, d1 = 0.f;
; #pragma unroll
;                 for (int x = 0; x < 16; x += 2) { d0 += q[x] * kf[x]; d1 += q[x + 1] * kf[x + 1]; }
;                 float d = d0 + d1;
;                 d += __shfl_xor(d, 1); d += __shfl_xor(d, 2); d += __shfl_xor(d, 4); s[i] = d; }
;             const float mn = fmaxf(fmaxf(fmaxf(mx, fmaxf(s[0], s[1])), fmaxf(s[2], s[3])), fmaxf(fmaxf(s[4], s[5]), fmaxf(s[6], s[7])));
;             const float al = __builtin_amdgcn_exp2f(mx - mn);
;             float p[8];
; #pragma unroll
;             for (int i = 0; i < 8; ++i) p[i] = __builtin_amdgcn_exp2f(s[i] - mn);
;             l = l * al + ((p[0] + p[1]) + (p[2] + p[3])) + ((p[4] + p[5]) + (p[6] + p[7]));
; #pragma unroll
;             for (int d = 0; d < 16; ++d) o[d] *= al;
; #pragma unroll
;             for (int i = 0; i < 8; ++i) { float vf[16]; unpack16_fp8(vv[i], vf);
; #pragma unroll
;                 for (int d = 0; d < 16; ++d) o[d] += p[i] * vf[d]; }
	v_cvt_pk_f32_fp8_e32 v[204:205], v188
	v_cvt_pk_f32_fp8_e32 v[206:207], v192
	v_pk_mul_f32 v[224:225], v[204:205], v[78:79]
	v_pk_mul_f32 v[226:227], v[206:207], v[78:79]
	v_cvt_pk_f32_fp8_sdwa v[208:209], v188 src0_sel:WORD_1
	v_cvt_pk_f32_fp8_sdwa v[210:211], v192 src0_sel:WORD_1
	v_pk_fma_f32 v[224:225], v[208:209], v[80:81], v[224:225]
	v_pk_fma_f32 v[226:227], v[210:211], v[80:81], v[226:227]
	v_cvt_pk_f32_fp8_e32 v[212:213], v189
	v_cvt_pk_f32_fp8_e32 v[214:215], v193
	v_pk_fma_f32 v[224:225], v[212:213], v[82:83], v[224:225]
	v_pk_fma_f32 v[226:227], v[214:215], v[82:83], v[226:227]
	v_cvt_pk_f32_fp8_sdwa v[216:217], v189 src0_sel:WORD_1
	v_cvt_pk_f32_fp8_sdwa v[218:219], v193 src0_sel:WORD_1
	v_pk_fma_f32 v[224:225], v[216:217], v[84:85], v[224:225]
	v_pk_fma_f32 v[226:227], v[218:219], v[84:85], v[226:227]
	v_cvt_pk_f32_fp8_e32 v[204:205], v190
	v_cvt_pk_f32_fp8_e32 v[206:207], v194
	v_pk_fma_f32 v[224:225], v[204:205], v[86:87], v[224:225]
	v_pk_fma_f32 v[226:227], v[206:207], v[86:87], v[226:227]
	v_cvt_pk_f32_fp8_sdwa v[208:209], v190 src0_sel:WORD_1
	v_cvt_pk_f32_fp8_sdwa v[210:211], v194 src0_sel:WORD_1
	v_pk_fma_f32 v[224:225], v[208:209], v[88:89], v[224:225]
	v_pk_fma_f32 v[226:227], v[210:211], v[88:89], v[226:227]
	v_cvt_pk_f32_fp8_e32 v[212:213], v191
	v_cvt_pk_f32_fp8_e32 v[214:215], v195
	v_pk_fma_f32 v[224:225], v[212:213], v[90:91], v[224:225]
	v_pk_fma_f32 v[226:227], v[214:215], v[90:91], v[226:227]
	v_cvt_pk_f32_fp8_sdwa v[216:217], v191 src0_sel:WORD_1
	v_cvt_pk_f32_fp8_sdwa v[218:219], v195 src0_sel:WORD_1
	v_pk_fma_f32 v[224:225], v[216:217], v[92:93], v[224:225]
	v_pk_fma_f32 v[226:227], v[218:219], v[92:93], v[226:227]
	v_add_f32_e32 v122, v220, v221
	v_add_f32_e32 v123, v222, v223
	v_add_f32_e32 v124, v224, v225
	v_add_f32_e32 v125, v226, v227
	v_add_f32_dpp v122, v122, v122 quad_perm:[1,0,3,2] row_mask:0xf bank_mask:0xf
	v_add_f32_dpp v123, v123, v123 quad_perm:[1,0,3,2] row_mask:0xf bank_mask:0xf
	v_add_f32_dpp v124, v124, v124 quad_perm:[1,0,3,2] row_mask:0xf bank_mask:0xf
	v_add_f32_dpp v125, v125, v125 quad_perm:[1,0,3,2] row_mask:0xf bank_mask:0xf
	v_add_f32_dpp v122, v122, v122 quad_perm:[2,3,0,1] row_mask:0xf bank_mask:0xf
	v_add_f32_dpp v123, v123, v123 quad_perm:[2,3,0,1] row_mask:0xf bank_mask:0xf
	v_add_f32_dpp v124, v124, v124 quad_perm:[2,3,0,1] row_mask:0xf bank_mask:0xf
	v_add_f32_dpp v125, v125, v125 quad_perm:[2,3,0,1] row_mask:0xf bank_mask:0xf
	v_add_f32_dpp v122, v122, v122 row_half_mirror row_mask:0xf bank_mask:0xf
	v_add_f32_dpp v123, v123, v123 row_half_mirror row_mask:0xf bank_mask:0xf
	v_add_f32_dpp v124, v124, v124 row_half_mirror row_mask:0xf bank_mask:0xf
	v_add_f32_dpp v125, v125, v125 row_half_mirror row_mask:0xf bank_mask:0xf
	v_max3_f32 v228, v110, v111, v112
	v_max3_f32 v229, v113, v114, v115
	v_max3_f32 v230, v116, v117, v118
	v_max3_f32 v231, v119, v120, v121
	v_max3_f32 v232, v122, v123, v124
	v_max3_f32 v233, v125, v109, v228
	v_max3_f32 v234, v229, v230, v231
	v_max3_f32 v235, v232, v233, v234
	v_sub_f32_e32 v236, v109, v235
	v_sub_f32_e32 v110, v110, v235
	v_sub_f32_e32 v111, v111, v235
	v_sub_f32_e32 v112, v112, v235
	v_sub_f32_e32 v113, v113, v235
	v_sub_f32_e32 v114, v114, v235
	v_sub_f32_e32 v115, v115, v235
	v_sub_f32_e32 v116, v116, v235
	v_sub_f32_e32 v117, v117, v235
	v_sub_f32_e32 v118, v118, v235
	v_sub_f32_e32 v119, v119, v235
	v_sub_f32_e32 v120, v120, v235
	v_sub_f32_e32 v121, v121, v235
	v_sub_f32_e32 v122, v122, v235
	v_sub_f32_e32 v123, v123, v235
	v_sub_f32_e32 v124, v124, v235
	v_sub_f32_e32 v125, v125, v235
	v_exp_f32_e32 v244, v236
	v_exp_f32_e32 v110, v110
	v_exp_f32_e32 v111, v111
	v_exp_f32_e32 v112, v112
	v_exp_f32_e32 v113, v113
	v_exp_f32_e32 v114, v114
	v_exp_f32_e32 v115, v115
	v_exp_f32_e32 v116, v116
	v_exp_f32_e32 v117, v117
	v_exp_f32_e32 v118, v118
	v_exp_f32_e32 v119, v119
	v_exp_f32_e32 v120, v120
	v_exp_f32_e32 v121, v121
	v_exp_f32_e32 v122, v122
	v_exp_f32_e32 v123, v123
	v_exp_f32_e32 v124, v124
	v_exp_f32_e32 v125, v125
	v_mov_b32_e32 v109, v235
	v_pk_mul_f32 v[62:63], v[62:63], v[244:245] op_sel_hi:[1,0]
	v_pk_mul_f32 v[64:65], v[64:65], v[244:245] op_sel_hi:[1,0]
	v_pk_mul_f32 v[66:67], v[66:67], v[244:245] op_sel_hi:[1,0]
	v_pk_mul_f32 v[68:69], v[68:69], v[244:245] op_sel_hi:[1,0]
	v_pk_mul_f32 v[70:71], v[70:71], v[244:245] op_sel_hi:[1,0]
	v_pk_mul_f32 v[72:73], v[72:73], v[244:245] op_sel_hi:[1,0]
	v_pk_mul_f32 v[74:75], v[74:75], v[244:245] op_sel_hi:[1,0]
	v_pk_mul_f32 v[76:77], v[76:77], v[244:245] op_sel_hi:[1,0]
	v_add_f32_e32 v228, v110, v111
	v_add_f32_e32 v229, v112, v113
	v_add_f32_e32 v230, v114, v115
	v_add_f32_e32 v231, v116, v117
	v_add_f32_e32 v232, v118, v119
	v_add_f32_e32 v233, v120, v121
	v_add_f32_e32 v234, v122, v123
	v_add_f32_e32 v235, v124, v125
	v_add_f32_e32 v228, v228, v229
	v_add_f32_e32 v230, v230, v231
	v_add_f32_e32 v232, v232, v233
	v_add_f32_e32 v234, v234, v235
	v_add_f32_e32 v228, v228, v230
	v_add_f32_e32 v232, v232, v234
	v_add_f32_e32 v228, v228, v232
	v_fma_f32 v108, v108, v244, v228
	s_waitcnt vmcnt(15)
	v_cvt_pk_f32_fp8_e32 v[204:205], v0
	v_cvt_pk_f32_fp8_sdwa v[206:207], v0 src0_sel:WORD_1
	v_pk_fma_f32 v[62:63], v[204:205], v[110:111], v[62:63] op_sel_hi:[1,0,1]
	v_pk_fma_f32 v[64:65], v[206:207], v[110:111], v[64:65] op_sel_hi:[1,0,1]
	v_cvt_pk_f32_fp8_e32 v[208:209], v1
	v_cvt_pk_f32_fp8_sdwa v[210:211], v1 src0_sel:WORD_1
	v_pk_fma_f32 v[66:67], v[208:209], v[110:111], v[66:67] op_sel_hi:[1,0,1]
	v_pk_fma_f32 v[68:69], v[210:211], v[110:111], v[68:69] op_sel_hi:[1,0,1]
	v_cvt_pk_f32_fp8_e32 v[212:213], v2
	v_cvt_pk_f32_fp8_sdwa v[214:215], v2 src0_sel:WORD_1
	v_pk_fma_f32 v[70:71], v[212:213], v[110:111], v[70:71] op_sel_hi:[1,0,1]
	v_pk_fma_f32 v[72:73], v[214:215], v[110:111], v[72:73] op_sel_hi:[1,0,1]
	v_cvt_pk_f32_fp8_e32 v[216:217], v3
	v_cvt_pk_f32_fp8_sdwa v[218:219], v3 src0_sel:WORD_1
	v_pk_fma_f32 v[74:75], v[216:217], v[110:111], v[74:75] op_sel_hi:[1,0,1]
	v_pk_fma_f32 v[76:77], v[218:219], v[110:111], v[76:77] op_sel_hi:[1,0,1]
	s_waitcnt vmcnt(14)
; __device__ __forceinline__ void attn_phase(const Args& a, unsigned char* lds, int lane, int wave) {
;     ...
;             for (int i = 0; i < 8; ++i) { float vf[16]; unpack16_fp8(vv[i], vf);
; #pragma unroll
;                 for (int d = 0; d < 16; ++d) o[d] += p[i] * vf[d]; }
	v_cvt_pk_f32_fp8_e32 v[204:205], v4
	v_cvt_pk_f32_fp8_sdwa v[206:207], v4 src0_sel:WORD_1
	v_pk_fma_f32 v[62:63], v[204:205], v[110:111], v[62:63] op_sel:[0,1,0] op_sel_hi:[1,1,1]
	v_pk_fma_f32 v[64:65], v[206:207], v[110:111], v[64:65] op_sel:[0,1,0] op_sel_hi:[1,1,1]
	v_cvt_pk_f32_fp8_e32 v[208:209], v5
	v_cvt_pk_f32_fp8_sdwa v[210:211], v5 src0_sel:WORD_1
	v_pk_fma_f32 v[66:67], v[208:209], v[110:111], v[66:67] op_sel:[0,1,0] op_sel_hi:[1,1,1]
	v_pk_fma_f32 v[68:69], v[210:211], v[110:111], v[68:69] op_sel:[0,1,0] op_sel_hi:[1,1,1]
	v_cvt_pk_f32_fp8_e32 v[212:213], v6
	v_cvt_pk_f32_fp8_sdwa v[214:215], v6 src0_sel:WORD_1
	v_pk_fma_f32 v[70:71], v[212:213], v[110:111], v[70:71] op_sel:[0,1,0] op_sel_hi:[1,1,1]
	v_pk_fma_f32 v[72:73], v[214:215], v[110:111], v[72:73] op_sel:[0,1,0] op_sel_hi:[1,1,1]
	v_cvt_pk_f32_fp8_e32 v[216:217], v7
	v_cvt_pk_f32_fp8_sdwa v[218:219], v7 src0_sel:WORD_1
	v_pk_fma_f32 v[74:75], v[216:217], v[110:111], v[74:75] op_sel:[0,1,0] op_sel_hi:[1,1,1]
	v_pk_fma_f32 v[76:77], v[218:219], v[110:111], v[76:77] op_sel:[0,1,0] op_sel_hi:[1,1,1]
	s_waitcnt vmcnt(13)
	v_cvt_pk_f32_fp8_e32 v[204:205], v8
	v_cvt_pk_f32_fp8_sdwa v[206:207], v8 src0_sel:WORD_1
	v_pk_fma_f32 v[62:63], v[204:205], v[112:113], v[62:63] op_sel_hi:[1,0,1]
	v_pk_fma_f32 v[64:65], v[206:207], v[112:113], v[64:65] op_sel_hi:[1,0,1]
	v_cvt_pk_f32_fp8_e32 v[208:209], v9
	v_cvt_pk_f32_fp8_sdwa v[210:211], v9 src0_sel:WORD_1
	v_pk_fma_f32 v[66:67], v[208:209], v[112:113], v[66:67] op_sel_hi:[1,0,1]
	v_pk_fma_f32 v[68:69], v[210:211], v[112:113], v[68:69] op_sel_hi:[1,0,1]
	v_cvt_pk_f32_fp8_e32 v[212:213], v10
	v_cvt_pk_f32_fp8_sdwa v[214:215], v10 src0_sel:WORD_1
	v_pk_fma_f32 v[70:71], v[212:213], v[112:113], v[70:71] op_sel_hi:[1,0,1]
	v_pk_fma_f32 v[72:73], v[214:215], v[112:113], v[72:73] op_sel_hi:[1,0,1]
	v_cvt_pk_f32_fp8_e32 v[216:217], v11
	v_cvt_pk_f32_fp8_sdwa v[218:219], v11 src0_sel:WORD_1
	v_pk_fma_f32 v[74:75], v[216:217], v[112:113], v[74:75] op_sel_hi:[1,0,1]
	v_pk_fma_f32 v[76:77], v[218:219], v[112:113], v[76:77] op_sel_hi:[1,0,1]
	s_waitcnt vmcnt(12)
	v_cvt_pk_f32_fp8_e32 v[204:205], v12
	v_cvt_pk_f32_fp8_sdwa v[206:207], v12 src0_sel:WORD_1
	v_pk_fma_f32 v[62:63], v[204:205], v[112:113], v[62:63] op_sel:[0,1,0] op_sel_hi:[1,1,1]
	v_pk_fma_f32 v[64:65], v[206:207], v[112:113], v[64:65] op_sel:[0,1,0] op_sel_hi:[1,1,1]
	v_cvt_pk_f32_fp8_e32 v[208:209], v13
	v_cvt_pk_f32_fp8_sdwa v[210:211], v13 src0_sel:WORD_1
	v_pk_fma_f32 v[66:67], v[208:209], v[112:113], v[66:67] op_sel:[0,1,0] op_sel_hi:[1,1,1]
	v_pk_fma_f32 v[68:69], v[210:211], v[112:113], v[68:69] op_sel:[0,1,0] op_sel_hi:[1,1,1]
	v_cvt_pk_f32_fp8_e32 v[212:213], v14
	v_cvt_pk_f32_fp8_sdwa v[214:215], v14 src0_sel:WORD_1
	v_pk_fma_f32 v[70:71], v[212:213], v[112:113], v[70:71] op_sel:[0,1,0] op_sel_hi:[1,1,1]
	v_pk_fma_f32 v[72:73], v[214:215], v[112:113], v[72:73] op_sel:[0,1,0] op_sel_hi:[1,1,1]
	v_cvt_pk_f32_fp8_e32 v[216:217], v15
	v_cvt_pk_f32_fp8_sdwa v[218:219], v15 src0_sel:WORD_1
	v_pk_fma_f32 v[74:75], v[216:217], v[112:113], v[74:75] op_sel:[0,1,0] op_sel_hi:[1,1,1]
	v_pk_fma_f32 v[76:77], v[218:219], v[112:113], v[76:77] op_sel:[0,1,0] op_sel_hi:[1,1,1]
	s_waitcnt vmcnt(11)
	v_cvt_pk_f32_fp8_e32 v[204:205], v16
	v_cvt_pk_f32_fp8_sdwa v[206:207], v16 src0_sel:WORD_1
	v_pk_fma_f32 v[62:63], v[204:205], v[114:115], v[62:63] op_sel_hi:[1,0,1]
	v_pk_fma_f32 v[64:65], v[206:207], v[114:115], v[64:65] op_sel_hi:[1,0,1]
	v_cvt_pk_f32_fp8_e32 v[208:209], v17
	v_cvt_pk_f32_fp8_sdwa v[210:211], v17 src0_sel:WORD_1
	v_pk_fma_f32 v[66:67], v[208:209], v[114:115], v[66:67] op_sel_hi:[1,0,1]
	v_pk_fma_f32 v[68:69], v[210:211], v[114:115], v[68:69] op_sel_hi:[1,0,1]
	v_cvt_pk_f32_fp8_e32 v[212:213], v18
	v_cvt_pk_f32_fp8_sdwa v[214:215], v18 src0_sel:WORD_1
	v_pk_fma_f32 v[70:71], v[212:213], v[114:115], v[70:71] op_sel_hi:[1,0,1]
	v_pk_fma_f32 v[72:73], v[214:215], v[114:115], v[72:73] op_sel_hi:[1,0,1]
	v_cvt_pk_f32_fp8_e32 v[216:217], v19
	v_cvt_pk_f32_fp8_sdwa v[218:219], v19 src0_sel:WORD_1
	v_pk_fma_f32 v[74:75], v[216:217], v[114:115], v[74:75] op_sel_hi:[1,0,1]
	v_pk_fma_f32 v[76:77], v[218:219], v[114:115], v[76:77] op_sel_hi:[1,0,1]
	s_waitcnt vmcnt(10)
	v_cvt_pk_f32_fp8_e32 v[204:205], v20
	v_cvt_pk_f32_fp8_sdwa v[206:207], v20 src0_sel:WORD_1
	v_pk_fma_f32 v[62:63], v[204:205], v[114:115], v[62:63] op_sel:[0,1,0] op_sel_hi:[1,1,1]
	v_pk_fma_f32 v[64:65], v[206:207], v[114:115], v[64:65] op_sel:[0,1,0] op_sel_hi:[1,1,1]
	v_cvt_pk_f32_fp8_e32 v[208:209], v21
	v_cvt_pk_f32_fp8_sdwa v[210:211], v21 src0_sel:WORD_1
	v_pk_fma_f32 v[66:67], v[208:209], v[114:115], v[66:67] op_sel:[0,1,0] op_sel_hi:[1,1,1]
	v_pk_fma_f32 v[68:69], v[210:211], v[114:115], v[68:69] op_sel:[0,1,0] op_sel_hi:[1,1,1]
	v_cvt_pk_f32_fp8_e32 v[212:213], v22
	v_cvt_pk_f32_fp8_sdwa v[214:215], v22 src0_sel:WORD_1
	v_pk_fma_f32 v[70:71], v[212:213], v[114:115], v[70:71] op_sel:[0,1,0] op_sel_hi:[1,1,1]
	v_pk_fma_f32 v[72:73], v[214:215], v[114:115], v[72:73] op_sel:[0,1,0] op_sel_hi:[1,1,1]
	v_cvt_pk_f32_fp8_e32 v[216:217], v23
	v_cvt_pk_f32_fp8_sdwa v[218:219], v23 src0_sel:WORD_1
	v_pk_fma_f32 v[74:75], v[216:217], v[114:115], v[74:75] op_sel:[0,1,0] op_sel_hi:[1,1,1]
	v_pk_fma_f32 v[76:77], v[218:219], v[114:115], v[76:77] op_sel:[0,1,0] op_sel_hi:[1,1,1]
	s_waitcnt vmcnt(9)
; __device__ __forceinline__ void attn_phase(const Args& a, unsigned char* lds, int lane, int wave) {
;     ...
;             for (int i = 0; i < 8; ++i) { float vf[16]; unpack16_fp8(vv[i], vf);
; #pragma unroll
;                 for (int d = 0; d < 16; ++d) o[d] += p[i] * vf[d]; }
	v_cvt_pk_f32_fp8_e32 v[204:205], v24
	v_cvt_pk_f32_fp8_sdwa v[206:207], v24 src0_sel:WORD_1
	v_pk_fma_f32 v[62:63], v[204:205], v[116:117], v[62:63] op_sel_hi:[1,0,1]
	v_pk_fma_f32 v[64:65], v[206:207], v[116:117], v[64:65] op_sel_hi:[1,0,1]
	v_cvt_pk_f32_fp8_e32 v[208:209], v25
	v_cvt_pk_f32_fp8_sdwa v[210:211], v25 src0_sel:WORD_1
	v_pk_fma_f32 v[66:67], v[208:209], v[116:117], v[66:67] op_sel_hi:[1,0,1]
	v_pk_fma_f32 v[68:69], v[210:211], v[116:117], v[68:69] op_sel_hi:[1,0,1]
	v_cvt_pk_f32_fp8_e32 v[212:213], v26
	v_cvt_pk_f32_fp8_sdwa v[214:215], v26 src0_sel:WORD_1
	v_pk_fma_f32 v[70:71], v[212:213], v[116:117], v[70:71] op_sel_hi:[1,0,1]
	v_pk_fma_f32 v[72:73], v[214:215], v[116:117], v[72:73] op_sel_hi:[1,0,1]
	v_cvt_pk_f32_fp8_e32 v[216:217], v27
	v_cvt_pk_f32_fp8_sdwa v[218:219], v27 src0_sel:WORD_1
	v_pk_fma_f32 v[74:75], v[216:217], v[116:117], v[74:75] op_sel_hi:[1,0,1]
	v_pk_fma_f32 v[76:77], v[218:219], v[116:117], v[76:77] op_sel_hi:[1,0,1]
	s_waitcnt vmcnt(8)
	v_cvt_pk_f32_fp8_e32 v[204:205], v28
	v_cvt_pk_f32_fp8_sdwa v[206:207], v28 src0_sel:WORD_1
	v_pk_fma_f32 v[62:63], v[204:205], v[116:117], v[62:63] op_sel:[0,1,0] op_sel_hi:[1,1,1]
	v_pk_fma_f32 v[64:65], v[206:207], v[116:117], v[64:65] op_sel:[0,1,0] op_sel_hi:[1,1,1]
	v_cvt_pk_f32_fp8_e32 v[208:209], v29
	v_cvt_pk_f32_fp8_sdwa v[210:211], v29 src0_sel:WORD_1
	v_pk_fma_f32 v[66:67], v[208:209], v[116:117], v[66:67] op_sel:[0,1,0] op_sel_hi:[1,1,1]
	v_pk_fma_f32 v[68:69], v[210:211], v[116:117], v[68:69] op_sel:[0,1,0] op_sel_hi:[1,1,1]
	v_cvt_pk_f32_fp8_e32 v[212:213], v30
	v_cvt_pk_f32_fp8_sdwa v[214:215], v30 src0_sel:WORD_1
	v_pk_fma_f32 v[70:71], v[212:213], v[116:117], v[70:71] op_sel:[0,1,0] op_sel_hi:[1,1,1]
	v_pk_fma_f32 v[72:73], v[214:215], v[116:117], v[72:73] op_sel:[0,1,0] op_sel_hi:[1,1,1]
	v_cvt_pk_f32_fp8_e32 v[216:217], v31
	v_cvt_pk_f32_fp8_sdwa v[218:219], v31 src0_sel:WORD_1
	v_pk_fma_f32 v[74:75], v[216:217], v[116:117], v[74:75] op_sel:[0,1,0] op_sel_hi:[1,1,1]
	v_pk_fma_f32 v[76:77], v[218:219], v[116:117], v[76:77] op_sel:[0,1,0] op_sel_hi:[1,1,1]
	s_waitcnt vmcnt(7)
	v_cvt_pk_f32_fp8_e32 v[204:205], v32
	v_cvt_pk_f32_fp8_sdwa v[206:207], v32 src0_sel:WORD_1
	v_pk_fma_f32 v[62:63], v[204:205], v[118:119], v[62:63] op_sel_hi:[1,0,1]
	v_pk_fma_f32 v[64:65], v[206:207], v[118:119], v[64:65] op_sel_hi:[1,0,1]
	v_cvt_pk_f32_fp8_e32 v[208:209], v33
	v_cvt_pk_f32_fp8_sdwa v[210:211], v33 src0_sel:WORD_1
	v_pk_fma_f32 v[66:67], v[208:209], v[118:119], v[66:67] op_sel_hi:[1,0,1]
	v_pk_fma_f32 v[68:69], v[210:211], v[118:119], v[68:69] op_sel_hi:[1,0,1]
	v_cvt_pk_f32_fp8_e32 v[212:213], v34
	v_cvt_pk_f32_fp8_sdwa v[214:215], v34 src0_sel:WORD_1
	v_pk_fma_f32 v[70:71], v[212:213], v[118:119], v[70:71] op_sel_hi:[1,0,1]
	v_pk_fma_f32 v[72:73], v[214:215], v[118:119], v[72:73] op_sel_hi:[1,0,1]
	v_cvt_pk_f32_fp8_e32 v[216:217], v35
	v_cvt_pk_f32_fp8_sdwa v[218:219], v35 src0_sel:WORD_1
	v_pk_fma_f32 v[74:75], v[216:217], v[118:119], v[74:75] op_sel_hi:[1,0,1]
	v_pk_fma_f32 v[76:77], v[218:219], v[118:119], v[76:77] op_sel_hi:[1,0,1]
	s_waitcnt vmcnt(6)
	v_cvt_pk_f32_fp8_e32 v[204:205], v36
	v_cvt_pk_f32_fp8_sdwa v[206:207], v36 src0_sel:WORD_1
	v_pk_fma_f32 v[62:63], v[204:205], v[118:119], v[62:63] op_sel:[0,1,0] op_sel_hi:[1,1,1]
	v_pk_fma_f32 v[64:65], v[206:207], v[118:119], v[64:65] op_sel:[0,1,0] op_sel_hi:[1,1,1]
	v_cvt_pk_f32_fp8_e32 v[208:209], v37
	v_cvt_pk_f32_fp8_sdwa v[210:211], v37 src0_sel:WORD_1
	v_pk_fma_f32 v[66:67], v[208:209], v[118:119], v[66:67] op_sel:[0,1,0] op_sel_hi:[1,1,1]
	v_pk_fma_f32 v[68:69], v[210:211], v[118:119], v[68:69] op_sel:[0,1,0] op_sel_hi:[1,1,1]
	v_cvt_pk_f32_fp8_e32 v[212:213], v38
	v_cvt_pk_f32_fp8_sdwa v[214:215], v38 src0_sel:WORD_1
	v_pk_fma_f32 v[70:71], v[212:213], v[118:119], v[70:71] op_sel:[0,1,0] op_sel_hi:[1,1,1]
	v_pk_fma_f32 v[72:73], v[214:215], v[118:119], v[72:73] op_sel:[0,1,0] op_sel_hi:[1,1,1]
	v_cvt_pk_f32_fp8_e32 v[216:217], v39
	v_cvt_pk_f32_fp8_sdwa v[218:219], v39 src0_sel:WORD_1
	v_pk_fma_f32 v[74:75], v[216:217], v[118:119], v[74:75] op_sel:[0,1,0] op_sel_hi:[1,1,1]
	v_pk_fma_f32 v[76:77], v[218:219], v[118:119], v[76:77] op_sel:[0,1,0] op_sel_hi:[1,1,1]
	s_waitcnt vmcnt(5)
	v_cvt_pk_f32_fp8_e32 v[204:205], v40
	v_cvt_pk_f32_fp8_sdwa v[206:207], v40 src0_sel:WORD_1
	v_pk_fma_f32 v[62:63], v[204:205], v[120:121], v[62:63] op_sel_hi:[1,0,1]
	v_pk_fma_f32 v[64:65], v[206:207], v[120:121], v[64:65] op_sel_hi:[1,0,1]
	v_cvt_pk_f32_fp8_e32 v[208:209], v41
	v_cvt_pk_f32_fp8_sdwa v[210:211], v41 src0_sel:WORD_1
	v_pk_fma_f32 v[66:67], v[208:209], v[120:121], v[66:67] op_sel_hi:[1,0,1]
	v_pk_fma_f32 v[68:69], v[210:211], v[120:121], v[68:69] op_sel_hi:[1,0,1]
	v_cvt_pk_f32_fp8_e32 v[212:213], v42
	v_cvt_pk_f32_fp8_sdwa v[214:215], v42 src0_sel:WORD_1
	v_pk_fma_f32 v[70:71], v[212:213], v[120:121], v[70:71] op_sel_hi:[1,0,1]
	v_pk_fma_f32 v[72:73], v[214:215], v[120:121], v[72:73] op_sel_hi:[1,0,1]
	v_cvt_pk_f32_fp8_e32 v[216:217], v43
	v_cvt_pk_f32_fp8_sdwa v[218:219], v43 src0_sel:WORD_1
	v_pk_fma_f32 v[74:75], v[216:217], v[120:121], v[74:75] op_sel_hi:[1,0,1]
	v_pk_fma_f32 v[76:77], v[218:219], v[120:121], v[76:77] op_sel_hi:[1,0,1]
	s_waitcnt vmcnt(4)
; __device__ __forceinline__ u32x4 pack8(const float* v) { u32x4 w; w.x = pk2(v[0], v[1]); w.y = pk2(v[2], v[3]); w.z = pk2(v[4], v[5]); w.w = pk2(v[6], v[7]); return w; }
; __device__ __forceinline__ void attn_phase(const Args& a, unsigned char* lds, int lane, int wave) {
;     ...
;     for (int t = gw; t < TT; t += NGW) {
;     ...
;             for (int i = 0; i < 8; ++i) { float vf[16]; unpack16_fp8(vv[i], vf);
; #pragma unroll
;                 for (int d = 0; d < 16; ++d) o[d] += p[i] * vf[d]; }
;             mx = mn;
;         }
;         const float il = 1.f / l;
; #pragma unroll
;         for (int d = 0; d < 16; ++d) o[d] *= il;
;         *(u32x4*)qp = pack8(o); *(u32x4*)(qp + 8) = pack8(o + 8);
	v_cvt_pk_f32_fp8_e32 v[204:205], v44
	v_cvt_pk_f32_fp8_sdwa v[206:207], v44 src0_sel:WORD_1
	v_pk_fma_f32 v[62:63], v[204:205], v[120:121], v[62:63] op_sel:[0,1,0] op_sel_hi:[1,1,1]
	v_pk_fma_f32 v[64:65], v[206:207], v[120:121], v[64:65] op_sel:[0,1,0] op_sel_hi:[1,1,1]
	v_cvt_pk_f32_fp8_e32 v[208:209], v45
	v_cvt_pk_f32_fp8_sdwa v[210:211], v45 src0_sel:WORD_1
	v_pk_fma_f32 v[66:67], v[208:209], v[120:121], v[66:67] op_sel:[0,1,0] op_sel_hi:[1,1,1]
	v_pk_fma_f32 v[68:69], v[210:211], v[120:121], v[68:69] op_sel:[0,1,0] op_sel_hi:[1,1,1]
	v_cvt_pk_f32_fp8_e32 v[212:213], v46
	v_cvt_pk_f32_fp8_sdwa v[214:215], v46 src0_sel:WORD_1
	v_pk_fma_f32 v[70:71], v[212:213], v[120:121], v[70:71] op_sel:[0,1,0] op_sel_hi:[1,1,1]
	v_pk_fma_f32 v[72:73], v[214:215], v[120:121], v[72:73] op_sel:[0,1,0] op_sel_hi:[1,1,1]
	v_cvt_pk_f32_fp8_e32 v[216:217], v47
	v_cvt_pk_f32_fp8_sdwa v[218:219], v47 src0_sel:WORD_1
	v_pk_fma_f32 v[74:75], v[216:217], v[120:121], v[74:75] op_sel:[0,1,0] op_sel_hi:[1,1,1]
	v_pk_fma_f32 v[76:77], v[218:219], v[120:121], v[76:77] op_sel:[0,1,0] op_sel_hi:[1,1,1]
	s_waitcnt vmcnt(3)
	v_cvt_pk_f32_fp8_e32 v[204:205], v48
	v_cvt_pk_f32_fp8_sdwa v[206:207], v48 src0_sel:WORD_1
	v_pk_fma_f32 v[62:63], v[204:205], v[122:123], v[62:63] op_sel_hi:[1,0,1]
	v_pk_fma_f32 v[64:65], v[206:207], v[122:123], v[64:65] op_sel_hi:[1,0,1]
	v_cvt_pk_f32_fp8_e32 v[208:209], v49
	v_cvt_pk_f32_fp8_sdwa v[210:211], v49 src0_sel:WORD_1
	v_pk_fma_f32 v[66:67], v[208:209], v[122:123], v[66:67] op_sel_hi:[1,0,1]
	v_pk_fma_f32 v[68:69], v[210:211], v[122:123], v[68:69] op_sel_hi:[1,0,1]
	v_cvt_pk_f32_fp8_e32 v[212:213], v50
	v_cvt_pk_f32_fp8_sdwa v[214:215], v50 src0_sel:WORD_1
	v_pk_fma_f32 v[70:71], v[212:213], v[122:123], v[70:71] op_sel_hi:[1,0,1]
	v_pk_fma_f32 v[72:73], v[214:215], v[122:123], v[72:73] op_sel_hi:[1,0,1]
	v_cvt_pk_f32_fp8_e32 v[216:217], v51
	v_cvt_pk_f32_fp8_sdwa v[218:219], v51 src0_sel:WORD_1
	v_pk_fma_f32 v[74:75], v[216:217], v[122:123], v[74:75] op_sel_hi:[1,0,1]
	v_pk_fma_f32 v[76:77], v[218:219], v[122:123], v[76:77] op_sel_hi:[1,0,1]
	s_waitcnt vmcnt(2)
	v_cvt_pk_f32_fp8_e32 v[204:205], v52
	v_cvt_pk_f32_fp8_sdwa v[206:207], v52 src0_sel:WORD_1
	v_pk_fma_f32 v[62:63], v[204:205], v[122:123], v[62:63] op_sel:[0,1,0] op_sel_hi:[1,1,1]
	v_pk_fma_f32 v[64:65], v[206:207], v[122:123], v[64:65] op_sel:[0,1,0] op_sel_hi:[1,1,1]
	v_cvt_pk_f32_fp8_e32 v[208:209], v53
	v_cvt_pk_f32_fp8_sdwa v[210:211], v53 src0_sel:WORD_1
	v_pk_fma_f32 v[66:67], v[208:209], v[122:123], v[66:67] op_sel:[0,1,0] op_sel_hi:[1,1,1]
	v_pk_fma_f32 v[68:69], v[210:211], v[122:123], v[68:69] op_sel:[0,1,0] op_sel_hi:[1,1,1]
	v_cvt_pk_f32_fp8_e32 v[212:213], v54
	v_cvt_pk_f32_fp8_sdwa v[214:215], v54 src0_sel:WORD_1
	v_pk_fma_f32 v[70:71], v[212:213], v[122:123], v[70:71] op_sel:[0,1,0] op_sel_hi:[1,1,1]
	v_pk_fma_f32 v[72:73], v[214:215], v[122:123], v[72:73] op_sel:[0,1,0] op_sel_hi:[1,1,1]
	v_cvt_pk_f32_fp8_e32 v[216:217], v55
	v_cvt_pk_f32_fp8_sdwa v[218:219], v55 src0_sel:WORD_1
	v_pk_fma_f32 v[74:75], v[216:217], v[122:123], v[74:75] op_sel:[0,1,0] op_sel_hi:[1,1,1]
	v_pk_fma_f32 v[76:77], v[218:219], v[122:123], v[76:77] op_sel:[0,1,0] op_sel_hi:[1,1,1]
	s_waitcnt vmcnt(1)
	v_cvt_pk_f32_fp8_e32 v[204:205], v196
	v_cvt_pk_f32_fp8_sdwa v[206:207], v196 src0_sel:WORD_1
	v_pk_fma_f32 v[62:63], v[204:205], v[124:125], v[62:63] op_sel_hi:[1,0,1]
	v_pk_fma_f32 v[64:65], v[206:207], v[124:125], v[64:65] op_sel_hi:[1,0,1]
	v_cvt_pk_f32_fp8_e32 v[208:209], v197
	v_cvt_pk_f32_fp8_sdwa v[210:211], v197 src0_sel:WORD_1
	v_pk_fma_f32 v[66:67], v[208:209], v[124:125], v[66:67] op_sel_hi:[1,0,1]
	v_pk_fma_f32 v[68:69], v[210:211], v[124:125], v[68:69] op_sel_hi:[1,0,1]
	v_cvt_pk_f32_fp8_e32 v[212:213], v198
	v_cvt_pk_f32_fp8_sdwa v[214:215], v198 src0_sel:WORD_1
	v_pk_fma_f32 v[70:71], v[212:213], v[124:125], v[70:71] op_sel_hi:[1,0,1]
	v_pk_fma_f32 v[72:73], v[214:215], v[124:125], v[72:73] op_sel_hi:[1,0,1]
	v_cvt_pk_f32_fp8_e32 v[216:217], v199
	v_cvt_pk_f32_fp8_sdwa v[218:219], v199 src0_sel:WORD_1
	v_pk_fma_f32 v[74:75], v[216:217], v[124:125], v[74:75] op_sel_hi:[1,0,1]
	v_pk_fma_f32 v[76:77], v[218:219], v[124:125], v[76:77] op_sel_hi:[1,0,1]
	s_waitcnt vmcnt(0)
	v_cvt_pk_f32_fp8_e32 v[204:205], v200
	v_cvt_pk_f32_fp8_sdwa v[206:207], v200 src0_sel:WORD_1
	v_pk_fma_f32 v[62:63], v[204:205], v[124:125], v[62:63] op_sel:[0,1,0] op_sel_hi:[1,1,1]
	v_pk_fma_f32 v[64:65], v[206:207], v[124:125], v[64:65] op_sel:[0,1,0] op_sel_hi:[1,1,1]
	v_cvt_pk_f32_fp8_e32 v[208:209], v201
	v_cvt_pk_f32_fp8_sdwa v[210:211], v201 src0_sel:WORD_1
	v_pk_fma_f32 v[66:67], v[208:209], v[124:125], v[66:67] op_sel:[0,1,0] op_sel_hi:[1,1,1]
	v_pk_fma_f32 v[68:69], v[210:211], v[124:125], v[68:69] op_sel:[0,1,0] op_sel_hi:[1,1,1]
	v_cvt_pk_f32_fp8_e32 v[212:213], v202
	v_cvt_pk_f32_fp8_sdwa v[214:215], v202 src0_sel:WORD_1
	v_pk_fma_f32 v[70:71], v[212:213], v[124:125], v[70:71] op_sel:[0,1,0] op_sel_hi:[1,1,1]
	v_pk_fma_f32 v[72:73], v[214:215], v[124:125], v[72:73] op_sel:[0,1,0] op_sel_hi:[1,1,1]
	v_cvt_pk_f32_fp8_e32 v[216:217], v203
	v_cvt_pk_f32_fp8_sdwa v[218:219], v203 src0_sel:WORD_1
	v_pk_fma_f32 v[74:75], v[216:217], v[124:125], v[74:75] op_sel:[0,1,0] op_sel_hi:[1,1,1]
	v_pk_fma_f32 v[76:77], v[218:219], v[124:125], v[76:77] op_sel:[0,1,0] op_sel_hi:[1,1,1]
	v_div_scale_f32 v0, s[0:1], v108, v108, 1.0
	v_rcp_f32_e32 v1, v0
	v_div_scale_f32 v2, vcc, 1.0, v108, 1.0
	s_add_i32 s2, s2, s28
	v_fma_f32 v3, -v0, v1, 1.0
	v_fmac_f32_e32 v1, v3, v1
	v_mul_f32_e32 v3, v2, v1
	v_fma_f32 v4, -v0, v3, v2
	v_fmac_f32_e32 v3, v4, v1
	v_fma_f32 v0, -v0, v3, v2
	v_div_fmas_f32 v0, v0, v1, v3
	v_div_fixup_f32 v0, v0, v108, 1.0
	v_pk_mul_f32 v[62:63], v[62:63], v[0:1] op_sel_hi:[1,0]
	v_pk_mul_f32 v[64:65], v[64:65], v[0:1] op_sel_hi:[1,0]
	v_pk_mul_f32 v[66:67], v[66:67], v[0:1] op_sel_hi:[1,0]
	v_pk_mul_f32 v[68:69], v[68:69], v[0:1] op_sel_hi:[1,0]
	v_pk_mul_f32 v[70:71], v[70:71], v[0:1] op_sel_hi:[1,0]
	v_pk_mul_f32 v[72:73], v[72:73], v[0:1] op_sel_hi:[1,0]
	v_pk_mul_f32 v[74:75], v[74:75], v[0:1] op_sel_hi:[1,0]
	v_pk_mul_f32 v[76:77], v[76:77], v[0:1] op_sel_hi:[1,0]
	v_cvt_pk_bf16_f32 v4, v62, v63
	v_cvt_pk_bf16_f32 v5, v64, v65
	v_cvt_pk_bf16_f32 v6, v66, v67
	v_cvt_pk_bf16_f32 v7, v68, v69
	v_cvt_pk_bf16_f32 v8, v70, v71
	v_cvt_pk_bf16_f32 v9, v72, v73
	v_cvt_pk_bf16_f32 v10, v74, v75
	v_cvt_pk_bf16_f32 v11, v76, v77
	global_store_dwordx4 v[60:61], v[4:7], off
	global_store_dwordx4 v[60:61], v[8:11], off offset:16
	s_cmpk_gt_i32 s2, 0x41ff
	s_cbranch_scc0 .Lat_q
	s_cmp_eq_u32 s98, 2
	s_cbranch_scc1 .LBB0_1934

; #define SEAM(k) do { if ((k) < hi) xcd_barrier(xbar); } while (0)
; __global__ void __launch_bounds__(512, 2) mega_fwd(Args a) {
;     ...
;     if (PHON(5)) {
;         attn_phase(a, lds, lane, wave); __syncthreads(); gla_g3(a, lds, tid, lane, wave);
;         SEAM(5); }
.LBB0_1934:
	s_cmp_eq_u32 s98, 1
	s_cbranch_scc0 .Lp5_seam
	s_mov_b32 s98, 2
	s_branch .Lp5_attn
